# attention KIND1 loop software-pipelined (QK of next tile overlapped with softmax packing, scalar-side DMA addressing); in-proj K loops: scalar-side LDS-DMA addressing with the DMA pieces issued betwee
# speedup vs baseline: 1.1997x; 1.0374x over previous
; DI int crow(int reg, int h) { return (reg & 3) + 8 * (reg >> 2) + 4 * h; }
; template <int KIND>
; DI void attn_unit(const Params& p, int l, int b, int head, int qt, int qcol, int kcol, int vfeat, int gcol, int mixcol,
;                   int t1, int n1, int t2, int n2, char* smem) {
;     ...
;     const int tq = qt * 128 + 32 * wave + r;
;     const size_t qrow = (size_t)b * TPB + tq;
;     const bf16_t* kbase = p.qkv + ((size_t)(kcol >> 6) * NTOK + (size_t)b * TPB) * 64;
;     const bf16_t* vbase = p.vT + ((size_t)b * 12 + (vfeat >> 6)) * 36 * 4096;
;     const int nt = n1 + n2;
;     bf16x8 qf[4];
;     {
;         const bf16_t* qp = p.qkv + ((size_t)(qcol >> 6) * NTOK + qrow) * 64 + 8 * h;
; #pragma unroll
;         for (int s = 0; s < 4; ++s) qf[s] = *(const bf16x8*)(qp + 16 * s);
;     }
;     int nrow = 0, r0w = 0, qc = 0, c0 = 0;
;     if (KIND == 2) {
;         nrow = 2 * qt + (wave >> 1); r0w = min(max(nrow - 4, 0), 24);
;         qc = 32 * (wave & 1) + r; c0 = min(max(qc - 8, 0), 48);
;         float* bias = (float*)(smem + ATT_BIAS);
;         for (int i = tid; i < 15 * 32; i += NTHREADS) { const int rr = i >> 5, cc = i & 31; bias[i] = cc < 31 ? p.rpb[((size_t)l * 6 + head) * 465 + rr * 31 + cc] * LOG2E : -INFINITY; }
;     }
;     int bcol[2][16];
;     if (KIND == 2) {
; #pragma unroll
;         for (int t = 0; t < 2; ++t)
; #pragma unroll
;             for (int e = 0; e < 16; ++e) {
;                 const int kc = 32 * t + crow(e, h);
;                 bcol[t][e] = ((unsigned)(kc - c0) < 16u) ? (kc - qc + 15) * 4 : 31 * 4;
;             }
;     }
;     f32x16 O0[2], O1[2];
; #pragma unroll
;     for (int t = 0; t < 2; ++t)
; #pragma unroll
;         for (int e = 0; e < 16; ++e) { O0[t][e] = 0.f; O1[t][e] = 0.f; }
;     float l0 = 0.f, l1 = 0.f;
;     const float zb = p.lam[8 + l * 4 + ((KIND == 1 && qcol >= 2048) ? 3 : KIND)];
;     f32x16 cz;
; #pragma unroll
;     for (int e = 0; e < 16; ++e) cz[e] = -zb;
;     const int kvoff = (8 * wave + (lane >> 3)) * 64 + (((lane & 7) ^ (((wave & 1) << 2) | (lane >> 4))) << 3);
;     const int xr = (r >> 1) & 7;
;     __syncthreads();
;     KV_ISSUE(t1, 0);
;     if (nt > 1) KV_ISSUE((1 < n1) ? t1 + 1 : t2 + (1 - n1), 1);
;     int sc = 0, sn = 2;
.LBB0_103:
	s_lshr_b32 s4, s4, 6
	s_lshl_b32 s6, s29, 7
	s_mul_i32 s29, s35, 0x900
	s_mulk_i32 s4, 0x4800
	s_mul_hi_i32 s7, s35, 0x900
	s_add_u32 s52, s29, s4
	s_addc_u32 s53, s7, 0
	s_lshl_b64 s[52:53], s[52:53], 7
	s_mul_i32 s56, s35, 12
	s_lshr_b32 s45, s45, 6
	s_mul_hi_i32 s47, s35, 12
	s_add_u32 s56, s56, s45
	v_mov_b32_e32 v7, v200
	s_addc_u32 s47, s47, 0
	s_load_dwordx4 s[40:43], s[0:1], 0xc0
	s_load_dwordx2 s[50:51], s[0:1], 0xf8
	v_ashrrev_i32_e32 v2, 6, v7
	s_mul_i32 s47, s47, 0x48000
	s_mul_hi_u32 s57, s56, 0x48000
	s_mul_i32 s58, s56, 0x48000
	s_lshr_b32 s56, s34, 6
	v_and_b32_e32 v6, 31, v7
	v_lshl_add_u32 v0, v2, 5, s6
	s_add_i32 s47, s57, s47
	s_mulk_i32 s56, 0x4800
	v_or_b32_e32 v0, v0, v6
	s_add_u32 s56, s29, s56
	v_ashrrev_i32_e32 v1, 31, v0
	s_addc_u32 s57, s7, 0
	v_lshl_add_u64 v[0:1], s[56:57], 0, v[0:1]
	s_waitcnt lgkmcnt(0)
	s_add_u32 s56, s40, s52
	s_addc_u32 s57, s41, s53
	s_cmpk_gt_u32 s34, 0x7ff
	s_cselect_b32 s34, 3, 1
	s_add_u32 s52, s34, s48
	s_addc_u32 s53, 0, s49
	v_bfe_u32 v102, v7, 5, 1
	v_lshlrev_b64 v[0:1], 7, v[0:1]
	s_lshl_b64 s[52:53], s[52:53], 2
	v_lshl_add_u64 v[0:1], s[40:41], 0, v[0:1]
	v_lshlrev_b32_e32 v192, 4, v102
	s_add_u32 s50, s50, s52
	v_lshl_add_u64 v[0:1], v[0:1], 0, v[192:193]
	s_addc_u32 s51, s51, s53
	global_load_dwordx4 v[92:95], v[0:1], off
	global_load_dwordx4 v[88:91], v[0:1], off offset:32
	global_load_dwordx4 v[84:87], v[0:1], off offset:64
	global_load_dwordx4 v[80:83], v[0:1], off offset:96
	v_lshlrev_b32_e32 v1, 3, v7
	global_load_dword v0, v193, s[50:51] offset:32
	s_movk_i32 s50, 0x1c0
	v_bfe_u32 v3, v7, 4, 2
	s_add_u32 s52, s42, s58
	s_addc_u32 s47, s43, s47
	s_lshl_b32 s46, s46, 13
	v_lshl_add_u32 v100, v7, 4, 32
	v_lshrrev_b32_e32 v12, 1, v7
	v_bfe_u32 v13, v7, 1, 3
	s_barrier
	s_mov_b32 s5, s75
	v_lshlrev_b32_e32 v105, 7, v6
	v_mov_b32_e32 v104, 0
	s_mov_b32 s34, 2
	v_add_u32_e32 v108, 32, v105
	v_mov_b32_e32 v32, 0
	v_mov_b32_e32 v33, v104
	v_mov_b32_e32 v34, v104
	v_mov_b32_e32 v35, v104
	v_mov_b32_e32 v36, v104
	v_mov_b32_e32 v37, v104
	v_mov_b32_e32 v38, v104
	v_mov_b32_e32 v39, v104
	v_mov_b32_e32 v40, v104
	v_mov_b32_e32 v41, v104
	v_mov_b32_e32 v42, v104
	v_mov_b32_e32 v43, v104
	v_mov_b32_e32 v44, v104
	v_mov_b32_e32 v45, v104
	v_mov_b32_e32 v46, v104
	v_mov_b32_e32 v47, v104
	v_mov_b32_e32 v6, v104
	v_mov_b32_e32 v14, v104
	v_mov_b32_e32 v15, v104
	s_waitcnt vmcnt(0)
	v_xor_b32_e32 v16, 0x80000000, v0
	v_lshlrev_b32_e32 v0, 9, v2
	v_lshlrev_b32_e32 v2, 2, v2
	v_and_or_b32 v0, v1, s50, v0
	v_and_b32_e32 v1, 7, v7
	v_and_b32_e32 v2, 4, v2
	v_bitop3_b32 v1, v2, v1, v3 bitop3:0x36
	v_lshl_or_b32 v0, v1, 3, v0
	s_add_u32 s50, s56, s46
	v_ashrrev_i32_e32 v1, 31, v0
	s_addc_u32 s51, s57, 0
	v_lshlrev_b64 v[0:1], 1, v[0:1]
	v_lshl_add_u64 v[4:5], s[50:51], 0, v[0:1]
	s_add_u32 s50, s52, s46
	s_addc_u32 s51, s47, 0
	v_readfirstlane_b32 s47, v100
	v_add_u32_e32 v7, 0x1000, v100
	s_mov_b32 m0, s47
	v_readfirstlane_b32 s47, v7
	v_add_u32_e32 v7, 0x2000, v100
	global_load_lds_dwordx4 v[4:5], off
	v_lshl_add_u64 v[8:9], v[4:5], 0, s[26:27]
	s_mov_b32 m0, s47
	v_readfirstlane_b32 s47, v7
	v_add_u32_e32 v7, 0x3000, v100
	v_lshl_add_u64 v[2:3], s[50:51], 0, v[0:1]
	global_load_lds_dwordx4 v[8:9], off
	s_mov_b32 m0, s47
	v_readfirstlane_b32 s47, v7
	v_add_u32_e32 v7, 0x4000, v100
	global_load_lds_dwordx4 v[2:3], off
	v_lshl_add_u64 v[8:9], v[2:3], 0, s[26:27]
	s_mov_b32 m0, s47
	v_readfirstlane_b32 s47, v7
	v_add_u32_e32 v7, 0x5000, v100
	global_load_lds_dwordx4 v[8:9], off
	v_lshl_add_u64 v[8:9], v[4:5], 0, s[16:17]
	s_mov_b32 m0, s47
	v_readfirstlane_b32 s47, v7
	global_load_lds_dwordx4 v[8:9], off
	v_lshl_add_u64 v[4:5], v[4:5], 0, s[90:91]
	s_mov_b32 m0, s47
	v_lshl_add_u64 v[10:11], v[2:3], 0, s[16:17]
	global_load_lds_dwordx4 v[4:5], off
	v_add_u32_e32 v4, 0x6000, v100
	v_lshl_add_u64 v[2:3], v[2:3], 0, s[90:91]
	v_readfirstlane_b32 s47, v4
	v_add_u32_e32 v4, 0x7000, v100
	s_mov_b32 m0, s47
	v_readfirstlane_b32 s47, v4
	global_load_lds_dwordx4 v[10:11], off
	s_mov_b32 m0, s47
	s_lshl_b32 s44, s44, 13
	global_load_lds_dwordx4 v[2:3], off
	s_add_u32 s44, s44, 0x2000
	s_mul_i32 s50, s35, 0x360000
	s_mul_hi_u32 s51, s45, 0x48000
	s_mul_i32 s45, s45, 0x48000
	s_mul_hi_i32 s47, s35, 0x360000
	s_add_u32 s45, s50, s45
	s_addc_u32 s47, s47, s51
	s_add_u32 s45, s45, s46
	s_addc_u32 s47, s47, 0
	s_add_u32 s42, s42, s45
	s_addc_u32 s43, s43, s47
	v_lshl_add_u64 v[96:97], s[42:43], 0, v[0:1]
	s_mov_b64 s[50:51], s[42:43]
	s_mul_hi_i32 s42, s35, 0x48000
	s_mul_i32 s35, s35, 0x48000
	s_add_u32 s35, s35, s46
	s_addc_u32 s42, s42, 0
	s_lshl_b64 s[4:5], s[4:5], 7
	v_bitop3_b32 v2, v102, v12, 7 bitop3:0x78
	s_add_u32 s4, s35, s4
	v_lshlrev_b32_e32 v107, 4, v2
	v_bitop3_b32 v2, v102, v13, 2 bitop3:0x36
	s_addc_u32 s5, s42, s5
	v_lshlrev_b32_e32 v106, 4, v2
	v_bitop3_b32 v2, v102, v13, 4 bitop3:0x36
	s_add_u32 s4, s40, s4
	v_lshlrev_b32_e32 v103, 4, v2
	v_bitop3_b32 v2, v102, v13, 6 bitop3:0x36
	s_addc_u32 s5, s41, s5
	v_mov_b32_e32 v17, v16
	v_mov_b32_e32 v18, v16
	v_mov_b32_e32 v19, v16
	v_mov_b32_e32 v20, v16
	v_mov_b32_e32 v21, v16
	v_mov_b32_e32 v22, v16
	v_mov_b32_e32 v23, v16
	v_mov_b32_e32 v24, v16
	v_mov_b32_e32 v25, v16
	v_mov_b32_e32 v26, v16
	v_mov_b32_e32 v27, v16
	v_mov_b32_e32 v28, v16
	v_mov_b32_e32 v29, v16
	v_mov_b32_e32 v30, v16
	v_mov_b32_e32 v31, v16
	v_lshlrev_b32_e32 v101, 4, v2
	v_lshl_add_u64 v[98:99], s[4:5], 0, v[0:1]
	s_mov_b64 s[52:53], s[4:5]
	s_mov_b32 s35, 0
	s_mov_b64 s[4:5], 0
	v_mov_b32_e32 v0, 0
	v_mov_b32_e32 v1, v104
	v_mov_b32_e32 v2, v104
	v_mov_b32_e32 v3, v104
	v_mov_b32_e32 v4, v104
	v_mov_b32_e32 v5, v104
	v_mov_b32_e32 v7, v104
	v_mov_b32_e32 v8, v104
	v_mov_b32_e32 v9, v104
	v_mov_b32_e32 v10, v104
	v_mov_b32_e32 v11, v104
	v_mov_b32_e32 v12, v104
	v_mov_b32_e32 v13, v104
	v_subrev_u32_e32 v246, s52, v98
	v_add_u32_e32 v247, 0x1000, v246
	v_readfirstlane_b32 s43, v100
	s_add_u32 s52, s52, 0x4000
	s_addc_u32 s53, s53, 0
	s_add_u32 s50, s50, 0x4000
	s_addc_u32 s51, s51, 0
	v_add_u32_e32 v194, v108, v107
	v_add_u32_e32 v195, v108, v106
	v_add_u32_e32 v196, v108, v103
	v_add_u32_e32 v197, v108, v101
	s_waitcnt vmcnt(4)
	s_barrier
; DI void softmax_tile(f32x16 (&S)[2], float& lsum) {
;     f2_t ps = {0.f, 0.f};
; #pragma unroll
;     for (int t = 0; t < 2; ++t)
; #pragma unroll
;         for (int e = 0; e < 16; e += 2) {
; template <int KIND>
; DI void attn_unit(const Params& p, int l, int b, int head, int qt, int qcol, int kcol, int vfeat, int gcol, int mixcol,
;                   int t1, int n1, int t2, int n2, char* smem) {
;     ...
;     for (int it = 0; it < nt; ++it) {
;         const int tile = (it < n1) ? t1 + it : t2 + (it - n1);
;         if (it + 1 < nt) asm volatile("s_waitcnt vmcnt(4)" ::: "memory"); else asm volatile("s_waitcnt vmcnt(0)" ::: "memory");
;         __builtin_amdgcn_s_barrier();
;         const char* sk = smem + sc * ATT_SLOT;
;         const char* sv = sk + ATT_V;
;         bool active = true;
;         if (KIND == 2 && tile < 32) active = (tile >= r0w) && (tile < r0w + 8);
;         bf16x8 kf[8], vf[8];
;         if (active) {
; #pragma unroll
;             for (int s = 0; s < 4; ++s)
; #pragma unroll
;                 for (int t = 0; t < 2; ++t) kf[2 * s + t] = *(const bf16x8*)(sk + (32 * t + r) * 128 + (((2 * s + h) ^ xr) << 4));
;         }
;         __builtin_amdgcn_sched_barrier(0);
;         if (it + 2 < nt) { const int nx = (it + 2 < n1) ? t1 + it + 2 : t2 + (it + 2 - n1); KV_ISSUE(nx, sn); }
;         sc = (sc == 2) ? 0 : sc + 1; sn = (sn == 2) ? 0 : sn + 1;
;         __builtin_amdgcn_sched_barrier(0);
;         if (active) {
;     ...
;             if (KIND == 0) {
;                 f32x16 S0[2], S1[2];
; #pragma unroll
;                 for (int t = 0; t < 2; ++t) { S0[t] = MFMA(kf[t], qf[0], cz); S1[t] = MFMA(kf[4 + t], qf[2], cz); }
; #pragma unroll
;                 for (int t = 0; t < 2; ++t) { S0[t] = MFMA(kf[2 + t], qf[1], S0[t]); S1[t] = MFMA(kf[6 + t], qf[3], S1[t]); }
;                 LOAD_VF();
;                 softmax_tile(S0, l0);
;                 pv_tile(S0, O0, vf);
;                 softmax_tile(S1, l1);
;                 pv_tile(S1, O1, vf);
;             } else {
;                 f32x16 S[2];
; #pragma unroll
;                 for (int t = 0; t < 2; ++t) S[t] = MFMA(kf[t], qf[0], cz);
; #pragma unroll
;                 for (int s = 1; s < 4; ++s)
; #pragma unroll
;                     for (int t = 0; t < 2; ++t) S[t] = MFMA(kf[2 * s + t], qf[s], S[t]);
;                 LOAD_VF();
	ds_read_b128 v[144:147], v194
	ds_read_b128 v[148:151], v194 offset:4096
	ds_read_b128 v[152:155], v195
	ds_read_b128 v[156:159], v195 offset:4096
	ds_read_b128 v[160:163], v196
	ds_read_b128 v[164:167], v196 offset:4096
	ds_read_b128 v[168:171], v197
	ds_read_b128 v[172:175], v197 offset:4096
	s_lshl_b32 s42, s34, 14
	s_add_i32 s42, s42, s43
	s_mov_b32 m0, s42
	s_nop 0
	global_load_lds_dwordx4 v246, s[52:53]
	s_add_u32 m0, s42, 0x1000
	s_nop 0
	global_load_lds_dwordx4 v247, s[52:53]
	s_add_u32 m0, s42, 0x2000
	s_nop 0
	global_load_lds_dwordx4 v246, s[50:51]
	s_add_u32 m0, s42, 0x3000
	s_nop 0
	global_load_lds_dwordx4 v247, s[50:51]
	s_add_u32 s52, s52, 0x2000
	s_addc_u32 s53, s53, 0
	s_add_u32 s50, s50, 0x2000
	s_addc_u32 s51, s51, 0
	s_mov_b32 s4, 0x2000
	s_waitcnt lgkmcnt(0)
	v_mfma_f32_32x32x16_bf16 v[64:79], v[144:147], v[92:95], v[16:31]
	v_mfma_f32_32x32x16_bf16 v[48:63], v[148:151], v[92:95], v[16:31]
	v_mfma_f32_32x32x16_bf16 v[64:79], v[152:155], v[88:91], v[64:79]
	v_mfma_f32_32x32x16_bf16 v[48:63], v[156:159], v[88:91], v[48:63]
	v_mfma_f32_32x32x16_bf16 v[64:79], v[160:163], v[84:87], v[64:79]
	v_mfma_f32_32x32x16_bf16 v[48:63], v[164:167], v[84:87], v[48:63]
	v_mfma_f32_32x32x16_bf16 v[64:79], v[168:171], v[80:83], v[64:79]
	v_mfma_f32_32x32x16_bf16 v[48:63], v[172:175], v[80:83], v[48:63]
	ds_read_b128 v[110:113], v194 offset:8192
	ds_read_b128 v[114:117], v194 offset:12288
	ds_read_b128 v[118:121], v195 offset:8192
	ds_read_b128 v[122:125], v195 offset:12288
	ds_read_b128 v[126:129], v196 offset:8192
	ds_read_b128 v[130:133], v196 offset:12288
	ds_read_b128 v[134:137], v197 offset:8192
	ds_read_b128 v[138:141], v197 offset:12288
	s_mov_b32 s35, 1
	s_mov_b32 s34, 2
	v_lshl_add_u32 v198, s35, 14, v108
	v_add_u32_e32 v194, v198, v107
	v_add_u32_e32 v195, v198, v106
	v_add_u32_e32 v196, v198, v103
	v_add_u32_e32 v197, v198, v101
	s_waitcnt lgkmcnt(0)
	s_waitcnt vmcnt(4)
	s_barrier
	ds_read_b128 v[144:147], v194
	ds_read_b128 v[148:151], v194 offset:4096
	ds_read_b128 v[152:155], v195
	ds_read_b128 v[156:159], v195 offset:4096
	ds_read_b128 v[160:163], v196
	ds_read_b128 v[164:167], v196 offset:4096
	ds_read_b128 v[168:171], v197
	ds_read_b128 v[172:175], v197 offset:4096
	s_lshl_b32 s42, s75, 14
	s_add_i32 s42, s42, s43
	s_mov_b32 m0, s42
	s_nop 0
	global_load_lds_dwordx4 v246, s[52:53]
	s_add_u32 m0, s42, 0x1000
	s_nop 0
	global_load_lds_dwordx4 v247, s[52:53]
	s_add_u32 m0, s42, 0x2000
	s_nop 0
	global_load_lds_dwordx4 v246, s[50:51]
	s_add_u32 m0, s42, 0x3000
	s_nop 0
	global_load_lds_dwordx4 v247, s[50:51]
	s_add_u32 s52, s52, 0x2000
	s_addc_u32 s53, s53, 0
	s_add_u32 s50, s50, 0x2000
	s_addc_u32 s51, s51, 0
	v_exp_f32_e32 v214, v64
	v_exp_f32_e32 v215, v65
	v_exp_f32_e32 v216, v66
	v_exp_f32_e32 v217, v67
	v_exp_f32_e32 v218, v68
	v_exp_f32_e32 v219, v69
	v_exp_f32_e32 v220, v70
	v_exp_f32_e32 v221, v71
	v_exp_f32_e32 v222, v72
	v_exp_f32_e32 v223, v73
	v_exp_f32_e32 v224, v74
	v_exp_f32_e32 v225, v75
	v_exp_f32_e32 v226, v76
	v_exp_f32_e32 v227, v77
	v_exp_f32_e32 v228, v78
	v_exp_f32_e32 v229, v79
	v_exp_f32_e32 v230, v48
	v_exp_f32_e32 v231, v49
	v_exp_f32_e32 v232, v50
	v_exp_f32_e32 v233, v51
	v_exp_f32_e32 v234, v52
	v_exp_f32_e32 v235, v53
	v_exp_f32_e32 v236, v54
	v_exp_f32_e32 v237, v55
	v_exp_f32_e32 v238, v56
	v_exp_f32_e32 v239, v57
	v_exp_f32_e32 v240, v58
	v_exp_f32_e32 v241, v59
	v_exp_f32_e32 v242, v60
	v_exp_f32_e32 v243, v61
	v_exp_f32_e32 v244, v62
	v_exp_f32_e32 v245, v63
.LBB0_104:
	v_cvt_pk_bf16_f32 v176, v214, v215
	v_cvt_pk_bf16_f32 v177, v216, v217
	v_add_f32_e32 v199, v214, v216
	v_add_f32_e32 v192, v215, v217
	v_add_f32_e32 v199, v218, v199
	v_add_f32_e32 v192, v219, v192
	s_waitcnt lgkmcnt(0)
	v_mfma_f32_32x32x16_bf16 v[64:79], v[144:147], v[92:95], v[16:31]
	v_cvt_pk_bf16_f32 v178, v218, v219
	v_cvt_pk_bf16_f32 v179, v220, v221
	v_add_f32_e32 v199, v220, v199
	v_add_f32_e32 v192, v221, v192
	v_add_f32_e32 v199, v222, v199
	v_mfma_f32_32x32x16_bf16 v[48:63], v[148:151], v[92:95], v[16:31]
	v_add_f32_e32 v192, v223, v192
	v_cvt_pk_bf16_f32 v180, v222, v223
	v_cvt_pk_bf16_f32 v181, v224, v225
	v_add_f32_e32 v199, v224, v199
	v_add_f32_e32 v192, v225, v192
	v_mfma_f32_32x32x16_bf16 v[64:79], v[152:155], v[88:91], v[64:79]
	v_add_f32_e32 v199, v226, v199
	v_add_f32_e32 v192, v227, v192
	v_cvt_pk_bf16_f32 v182, v226, v227
	v_cvt_pk_bf16_f32 v183, v228, v229
	v_add_f32_e32 v199, v228, v199
	v_mfma_f32_32x32x16_bf16 v[48:63], v[156:159], v[88:91], v[48:63]
	v_add_f32_e32 v192, v229, v192
	v_add_f32_e32 v199, v230, v199
	v_add_f32_e32 v192, v231, v192
	v_cvt_pk_bf16_f32 v184, v230, v231
	v_cvt_pk_bf16_f32 v185, v232, v233
	v_mfma_f32_32x32x16_bf16 v[64:79], v[160:163], v[84:87], v[64:79]
	v_add_f32_e32 v199, v232, v199
	v_add_f32_e32 v192, v233, v192
	v_add_f32_e32 v199, v234, v199
	v_add_f32_e32 v192, v235, v192
	v_cvt_pk_bf16_f32 v186, v234, v235
	v_mfma_f32_32x32x16_bf16 v[48:63], v[164:167], v[84:87], v[48:63]
	v_cvt_pk_bf16_f32 v187, v236, v237
	v_add_f32_e32 v199, v236, v199
	v_add_f32_e32 v192, v237, v192
	v_add_f32_e32 v199, v238, v199
	v_add_f32_e32 v192, v239, v192
	v_mfma_f32_32x32x16_bf16 v[64:79], v[168:171], v[80:83], v[64:79]
	v_cvt_pk_bf16_f32 v188, v238, v239
	v_cvt_pk_bf16_f32 v189, v240, v241
	v_add_f32_e32 v199, v240, v199
	v_add_f32_e32 v192, v241, v192
	v_add_f32_e32 v199, v242, v199
	v_add_f32_e32 v192, v243, v192
	v_mfma_f32_32x32x16_bf16 v[48:63], v[172:175], v[80:83], v[48:63]
	v_cvt_pk_bf16_f32 v190, v242, v243
	v_cvt_pk_bf16_f32 v191, v244, v245
	v_add_f32_e32 v199, v244, v199
	v_add_f32_e32 v192, v245, v192
	v_add_f32_e32 v199, v199, v192
	v_add_f32_e32 v104, v104, v199
; DI void softmax_tile(f32x16 (&S)[2], float& lsum) {
;     f2_t ps = {0.f, 0.f};
; #pragma unroll
;     for (int t = 0; t < 2; ++t)
; #pragma unroll
;         for (int e = 0; e < 16; e += 2) {
; template <int KIND>
; DI void attn_unit(const Params& p, int l, int b, int head, int qt, int qcol, int kcol, int vfeat, int gcol, int mixcol,
;                   int t1, int n1, int t2, int n2, char* smem) {
;     ...
;     for (int it = 0; it < nt; ++it) {
;         const int tile = (it < n1) ? t1 + it : t2 + (it - n1);
;         if (it + 1 < nt) asm volatile("s_waitcnt vmcnt(4)" ::: "memory"); else asm volatile("s_waitcnt vmcnt(0)" ::: "memory");
;         __builtin_amdgcn_s_barrier();
;         const char* sk = smem + sc * ATT_SLOT;
;         const char* sv = sk + ATT_V;
;         bool active = true;
;         if (KIND == 2 && tile < 32) active = (tile >= r0w) && (tile < r0w + 8);
;         bf16x8 kf[8], vf[8];
;         if (active) {
; #pragma unroll
;             for (int s = 0; s < 4; ++s)
; #pragma unroll
;                 for (int t = 0; t < 2; ++t) kf[2 * s + t] = *(const bf16x8*)(sk + (32 * t + r) * 128 + (((2 * s + h) ^ xr) << 4));
;         }
;         __builtin_amdgcn_sched_barrier(0);
;         if (it + 2 < nt) { const int nx = (it + 2 < n1) ? t1 + it + 2 : t2 + (it + 2 - n1); KV_ISSUE(nx, sn); }
;         sc = (sc == 2) ? 0 : sc + 1; sn = (sn == 2) ? 0 : sn + 1;
;         __builtin_amdgcn_sched_barrier(0);
;         if (active) {
;     ...
;             if (KIND == 0) {
;                 f32x16 S0[2], S1[2];
; #pragma unroll
;                 for (int t = 0; t < 2; ++t) { S0[t] = MFMA(kf[t], qf[0], cz); S1[t] = MFMA(kf[4 + t], qf[2], cz); }
; #pragma unroll
;                 for (int t = 0; t < 2; ++t) { S0[t] = MFMA(kf[2 + t], qf[1], S0[t]); S1[t] = MFMA(kf[6 + t], qf[3], S1[t]); }
;                 LOAD_VF();
;                 softmax_tile(S0, l0);
;                 pv_tile(S0, O0, vf);
;                 softmax_tile(S1, l1);
;                 pv_tile(S1, O1, vf);
;             } else {
;                 f32x16 S[2];
; #pragma unroll
;                 for (int t = 0; t < 2; ++t) S[t] = MFMA(kf[t], qf[0], cz);
; #pragma unroll
;                 for (int s = 1; s < 4; ++s)
; #pragma unroll
;                     for (int t = 0; t < 2; ++t) S[t] = MFMA(kf[2 * s + t], qf[s], S[t]);
;                 LOAD_VF();
	v_mfma_f32_32x32x16_bf16 v[32:47], v[110:113], v[176:179], v[32:47]
	v_exp_f32_e32 v214, v64
	v_exp_f32_e32 v215, v65
	v_exp_f32_e32 v216, v66
	v_mfma_f32_32x32x16_bf16 v[0:15], v[114:117], v[176:179], v[0:15]
	v_exp_f32_e32 v217, v67
	v_exp_f32_e32 v218, v68
	v_exp_f32_e32 v219, v69
	ds_read_b128 v[110:113], v194 offset:8192
	ds_read_b128 v[114:117], v194 offset:12288
	v_mfma_f32_32x32x16_bf16 v[32:47], v[118:121], v[180:183], v[32:47]
	v_exp_f32_e32 v220, v70
	v_exp_f32_e32 v221, v71
	v_exp_f32_e32 v222, v72
	v_mfma_f32_32x32x16_bf16 v[0:15], v[122:125], v[180:183], v[0:15]
	v_exp_f32_e32 v223, v73
	v_exp_f32_e32 v224, v74
	v_exp_f32_e32 v225, v75
	ds_read_b128 v[118:121], v195 offset:8192
	ds_read_b128 v[122:125], v195 offset:12288
	v_mfma_f32_32x32x16_bf16 v[32:47], v[126:129], v[184:187], v[32:47]
	v_exp_f32_e32 v226, v76
	v_exp_f32_e32 v227, v77
	v_exp_f32_e32 v228, v78
	v_mfma_f32_32x32x16_bf16 v[0:15], v[130:133], v[184:187], v[0:15]
	v_exp_f32_e32 v229, v79
	v_exp_f32_e32 v230, v48
	v_exp_f32_e32 v231, v49
	ds_read_b128 v[126:129], v196 offset:8192
	ds_read_b128 v[130:133], v196 offset:12288
	v_mfma_f32_32x32x16_bf16 v[32:47], v[134:137], v[188:191], v[32:47]
	v_exp_f32_e32 v232, v50
	v_exp_f32_e32 v233, v51
	v_exp_f32_e32 v234, v52
	v_mfma_f32_32x32x16_bf16 v[0:15], v[138:141], v[188:191], v[0:15]
	v_exp_f32_e32 v235, v53
	v_exp_f32_e32 v236, v54
	v_exp_f32_e32 v237, v55
	ds_read_b128 v[134:137], v197 offset:8192
	ds_read_b128 v[138:141], v197 offset:12288
	s_add_u32 s4, s4, 0x2000
	s_addc_u32 s5, s5, 0
	s_cmp_eq_u32 s44, s4
	s_cbranch_scc1 .Lk1_drain
	v_lshl_add_u32 v198, s34, 14, v108
	v_add_u32_e32 v194, v198, v107
	v_add_u32_e32 v195, v198, v106
	v_add_u32_e32 v196, v198, v103
	v_add_u32_e32 v197, v198, v101
	v_exp_f32_e32 v238, v56
	v_exp_f32_e32 v239, v57
	v_exp_f32_e32 v240, v58
	v_exp_f32_e32 v241, v59
	s_lshl_b32 s42, s35, 14
	s_add_i32 s42, s42, s43
	s_waitcnt lgkmcnt(0)
	s_waitcnt vmcnt(4)
	s_barrier
	ds_read_b128 v[144:147], v194
	s_mov_b32 m0, s42
	ds_read_b128 v[148:151], v194 offset:4096
	global_load_lds_dwordx4 v246, s[52:53]
	v_exp_f32_e32 v242, v60
	ds_read_b128 v[152:155], v195
	s_add_u32 m0, s42, 0x1000
	ds_read_b128 v[156:159], v195 offset:4096
	global_load_lds_dwordx4 v247, s[52:53]
	v_exp_f32_e32 v243, v61
	ds_read_b128 v[160:163], v196
	s_add_u32 m0, s42, 0x2000
	ds_read_b128 v[164:167], v196 offset:4096
	global_load_lds_dwordx4 v246, s[50:51]
	v_exp_f32_e32 v244, v62
	ds_read_b128 v[168:171], v197
	s_add_u32 m0, s42, 0x3000
	ds_read_b128 v[172:175], v197 offset:4096
	global_load_lds_dwordx4 v247, s[50:51]
	v_exp_f32_e32 v245, v63
	s_add_u32 s52, s52, 0x2000
	s_addc_u32 s53, s53, 0
	s_add_u32 s50, s50, 0x2000
	s_addc_u32 s51, s51, 0
	s_mov_b32 s35, s34
	s_add_i32 s42, s34, 1
	s_cmp_lg_u32 s34, 2
	s_cselect_b32 s34, s42, 0
	s_branch .LBB0_104
.Lk1_drain:
	s_mov_b32 s35, s34
	v_exp_f32_e32 v238, v56
	v_exp_f32_e32 v239, v57
	v_exp_f32_e32 v240, v58
	v_exp_f32_e32 v241, v59
	v_exp_f32_e32 v242, v60
	v_exp_f32_e32 v243, v61
	v_exp_f32_e32 v244, v62
	v_exp_f32_e32 v245, v63
	v_cvt_pk_bf16_f32 v176, v214, v215
	v_cvt_pk_bf16_f32 v177, v216, v217
	v_add_f32_e32 v199, v214, v216
	v_add_f32_e32 v192, v215, v217
	v_add_f32_e32 v199, v218, v199
	v_add_f32_e32 v192, v219, v192
	v_cvt_pk_bf16_f32 v178, v218, v219
	v_cvt_pk_bf16_f32 v179, v220, v221
	v_add_f32_e32 v199, v220, v199
	v_add_f32_e32 v192, v221, v192
	v_add_f32_e32 v199, v222, v199
	v_add_f32_e32 v192, v223, v192
	v_cvt_pk_bf16_f32 v180, v222, v223
	v_cvt_pk_bf16_f32 v181, v224, v225
	v_add_f32_e32 v199, v224, v199
	v_add_f32_e32 v192, v225, v192
	v_add_f32_e32 v199, v226, v199
	v_add_f32_e32 v192, v227, v192
	v_cvt_pk_bf16_f32 v182, v226, v227
	v_cvt_pk_bf16_f32 v183, v228, v229
	v_add_f32_e32 v199, v228, v199
	v_add_f32_e32 v192, v229, v192
	v_add_f32_e32 v199, v230, v199
	v_add_f32_e32 v192, v231, v192
	v_cvt_pk_bf16_f32 v184, v230, v231
	v_cvt_pk_bf16_f32 v185, v232, v233
	v_add_f32_e32 v199, v232, v199
	v_add_f32_e32 v192, v233, v192
	v_add_f32_e32 v199, v234, v199
	v_add_f32_e32 v192, v235, v192
	v_cvt_pk_bf16_f32 v186, v234, v235
	v_cvt_pk_bf16_f32 v187, v236, v237
	v_add_f32_e32 v199, v236, v199
	v_add_f32_e32 v192, v237, v192
	v_add_f32_e32 v199, v238, v199
	v_add_f32_e32 v192, v239, v192
	v_cvt_pk_bf16_f32 v188, v238, v239
	v_cvt_pk_bf16_f32 v189, v240, v241
	v_add_f32_e32 v199, v240, v199
	v_add_f32_e32 v192, v241, v192
	v_add_f32_e32 v199, v242, v199
	v_add_f32_e32 v192, v243, v192
	v_cvt_pk_bf16_f32 v190, v242, v243
	v_cvt_pk_bf16_f32 v191, v244, v245
	v_add_f32_e32 v199, v244, v199
	v_add_f32_e32 v192, v245, v192
	v_add_f32_e32 v199, v199, v192
	v_add_f32_e32 v104, v104, v199
	s_waitcnt lgkmcnt(0)
	v_mfma_f32_32x32x16_bf16 v[32:47], v[110:113], v[176:179], v[32:47]
	v_mfma_f32_32x32x16_bf16 v[0:15], v[114:117], v[176:179], v[0:15]
	v_mfma_f32_32x32x16_bf16 v[32:47], v[118:121], v[180:183], v[32:47]
	v_mfma_f32_32x32x16_bf16 v[0:15], v[122:125], v[180:183], v[0:15]
	v_mfma_f32_32x32x16_bf16 v[32:47], v[126:129], v[184:187], v[32:47]
	v_mfma_f32_32x32x16_bf16 v[0:15], v[130:133], v[184:187], v[0:15]
	v_mfma_f32_32x32x16_bf16 v[32:47], v[134:137], v[188:191], v[32:47]
	v_mfma_f32_32x32x16_bf16 v[0:15], v[138:141], v[188:191], v[0:15]
	s_lshl_b32 s4, s35, 14
	s_add_i32 s5, s4, 32
	v_add_u32_e32 v52, s5, v105
	v_add_u32_e32 v100, v52, v107
	v_add_u32_e32 v132, v52, v106
	v_add_u32_e32 v133, v52, v103
	v_add_u32_e32 v134, v52, v101
	s_waitcnt vmcnt(4)
	s_barrier
; template <int KIND>
; DI void attn_unit(const Params& p, int l, int b, int head, int qt, int qcol, int kcol, int vfeat, int gcol, int mixcol,
;                   int t1, int n1, int t2, int n2, char* smem) {
;     ...
;     for (int it = 0; it < nt; ++it) {
;         const int tile = (it < n1) ? t1 + it : t2 + (it - n1);
;         if (it + 1 < nt) asm volatile("s_waitcnt vmcnt(4)" ::: "memory"); else asm volatile("s_waitcnt vmcnt(0)" ::: "memory");
;         __builtin_amdgcn_s_barrier();
;         const char* sk = smem + sc * ATT_SLOT;
;         const char* sv = sk + ATT_V;
;         bool active = true;
;         if (KIND == 2 && tile < 32) active = (tile >= r0w) && (tile < r0w + 8);
;         bf16x8 kf[8], vf[8];
;         if (active) {
; #pragma unroll
;             for (int s = 0; s < 4; ++s)
; #pragma unroll
;                 for (int t = 0; t < 2; ++t) kf[2 * s + t] = *(const bf16x8*)(sk + (32 * t + r) * 128 + (((2 * s + h) ^ xr) << 4));
;         }
;         __builtin_amdgcn_sched_barrier(0);
;         if (it + 2 < nt) { const int nx = (it + 2 < n1) ? t1 + it + 2 : t2 + (it + 2 - n1); KV_ISSUE(nx, sn); }
;         sc = (sc == 2) ? 0 : sc + 1; sn = (sn == 2) ? 0 : sn + 1;
;         __builtin_amdgcn_sched_barrier(0);
;         if (active) {
;     ...
;             if (KIND == 0) {
;                 f32x16 S0[2], S1[2];
; #pragma unroll
;                 for (int t = 0; t < 2; ++t) { S0[t] = MFMA(kf[t], qf[0], cz); S1[t] = MFMA(kf[4 + t], qf[2], cz); }
; #pragma unroll
;                 for (int t = 0; t < 2; ++t) { S0[t] = MFMA(kf[2 + t], qf[1], S0[t]); S1[t] = MFMA(kf[6 + t], qf[3], S1[t]); }
;                 LOAD_VF();
;                 softmax_tile(S0, l0);
;                 pv_tile(S0, O0, vf);
;                 softmax_tile(S1, l1);
;                 pv_tile(S1, O1, vf);
;             } else {
;                 f32x16 S[2];
; #pragma unroll
;                 for (int t = 0; t < 2; ++t) S[t] = MFMA(kf[t], qf[0], cz);
; #pragma unroll
;                 for (int s = 1; s < 4; ++s)
; #pragma unroll
;                     for (int t = 0; t < 2; ++t) S[t] = MFMA(kf[2 * s + t], qf[s], S[t]);
;                 LOAD_VF();
;                 if (KIND == 2 && tile < 32) {
;                     const char* brow = smem + ATT_BIAS + (tile - nrow + 7) * 128;
; #pragma unroll
;                     for (int t = 0; t < 2; ++t)
; #pragma unroll
	ds_read_b128 v[48:51], v100
	ds_read_b128 v[96:99], v100 offset:4096
	ds_read_b128 v[108:111], v132
	ds_read_b128 v[112:115], v132 offset:4096
	ds_read_b128 v[116:119], v133
	ds_read_b128 v[120:123], v133 offset:4096
	ds_read_b128 v[124:127], v134
	ds_read_b128 v[128:131], v134 offset:4096
	s_waitcnt lgkmcnt(0)
	v_mfma_f32_32x32x16_bf16 v[64:79], v[48:51], v[92:95], v[16:31]
	v_mfma_f32_32x32x16_bf16 v[48:63], v[96:99], v[92:95], v[16:31]
	v_mfma_f32_32x32x16_bf16 v[64:79], v[108:111], v[88:91], v[64:79]
	v_mfma_f32_32x32x16_bf16 v[48:63], v[112:115], v[88:91], v[48:63]
	v_mfma_f32_32x32x16_bf16 v[64:79], v[116:119], v[84:87], v[64:79]
	v_mfma_f32_32x32x16_bf16 v[48:63], v[120:123], v[84:87], v[48:63]
	v_mfma_f32_32x32x16_bf16 v[64:79], v[124:127], v[80:83], v[64:79]
	v_mfma_f32_32x32x16_bf16 v[48:63], v[128:131], v[80:83], v[48:63]
	ds_read_b128 v[96:99], v100 offset:8192
	ds_read_b128 v[108:111], v100 offset:12288
	ds_read_b128 v[112:115], v132 offset:8192
	ds_read_b128 v[116:119], v132 offset:12288
	ds_read_b128 v[120:123], v133 offset:8192
	ds_read_b128 v[124:127], v133 offset:12288
	ds_read_b128 v[128:131], v134 offset:8192
	ds_read_b128 v[132:135], v134 offset:12288
	s_nop 2
	v_exp_f32_e32 v64, v64
	v_exp_f32_e32 v65, v65
	v_exp_f32_e32 v66, v66
	v_exp_f32_e32 v67, v67
	v_exp_f32_e32 v68, v68
	v_exp_f32_e32 v69, v69
	v_exp_f32_e32 v70, v70
	v_exp_f32_e32 v71, v71
	v_add_f32_e64 v136, v64, 0
	v_add_f32_e64 v137, v65, 0
	v_exp_f32_e32 v72, v72
	v_add_f32_e64 v136, v66, v136
	v_add_f32_e64 v137, v67, v137
	v_exp_f32_e32 v73, v73
	v_cvt_pk_bf16_f32 v64, v64, v65
	v_cvt_pk_bf16_f32 v65, v66, v67
	v_cvt_pk_bf16_f32 v66, v68, v69
	v_cvt_pk_bf16_f32 v67, v70, v71
	v_exp_f32_e32 v74, v74
	v_exp_f32_e32 v75, v75
	s_waitcnt lgkmcnt(0)
	v_mfma_f32_32x32x16_bf16 v[32:47], v[96:99], v[64:67], v[32:47]
	v_add_f32_e64 v136, v68, v136
	v_add_f32_e64 v137, v69, v137
	v_exp_f32_e32 v68, v76
	v_exp_f32_e32 v69, v77
	v_add_f32_e64 v136, v70, v136
	v_add_f32_e64 v137, v71, v137
	v_exp_f32_e32 v70, v78
	v_exp_f32_e32 v71, v79
	v_add_f32_e64 v136, v72, v136
	v_add_f32_e64 v137, v73, v137
	v_mfma_f32_32x32x16_bf16 v[0:15], v[108:111], v[64:67], v[0:15]
	v_exp_f32_e32 v48, v48
	v_exp_f32_e32 v49, v49
	v_add_f32_e64 v136, v74, v136
	v_add_f32_e64 v137, v75, v137
	v_exp_f32_e32 v50, v50
	v_add_f32_e64 v76, v68, v136
	v_add_f32_e64 v77, v69, v137
	v_cvt_pk_bf16_f32 v66, v68, v69
	v_add_f32_e64 v64, v70, v76
	v_add_f32_e64 v65, v71, v77
	v_cvt_pk_bf16_f32 v67, v70, v71
	v_add_f32_e64 v76, v48, v64
	v_add_f32_e64 v77, v49, v65
	v_cvt_pk_bf16_f32 v64, v72, v73
	v_cvt_pk_bf16_f32 v65, v74, v75
	v_exp_f32_e32 v51, v51
	v_exp_f32_e32 v52, v52
	v_mfma_f32_32x32x16_bf16 v[32:47], v[112:115], v[64:67], v[32:47]
	v_exp_f32_e32 v53, v53
	v_exp_f32_e32 v54, v54
	v_exp_f32_e32 v55, v55
	v_add_f32_e64 v68, v50, v76
	v_add_f32_e64 v69, v51, v77
	v_exp_f32_e32 v56, v56
	v_add_f32_e64 v68, v52, v68
	v_add_f32_e64 v69, v53, v69
	v_exp_f32_e32 v57, v57
	v_mfma_f32_32x32x16_bf16 v[0:15], v[116:119], v[64:67], v[0:15]
	v_add_f32_e64 v64, v54, v68
	v_add_f32_e64 v65, v55, v69
	v_cvt_pk_bf16_f32 v48, v48, v49
	v_cvt_pk_bf16_f32 v49, v50, v51
	v_cvt_pk_bf16_f32 v51, v54, v55
	v_exp_f32_e32 v54, v58
	v_exp_f32_e32 v55, v59
	s_addk_i32 s4, 0x4000
	s_cmp_lg_u32 s35, 2
	v_cvt_pk_bf16_f32 v50, v52, v53
	s_cselect_b32 s4, s4, 0
	v_add_f32_e64 v52, v56, v64
	v_add_f32_e64 v53, v57, v65
	v_mfma_f32_32x32x16_bf16 v[32:47], v[120:123], v[48:51], v[32:47]
	s_add_i32 s4, s4, 32
	v_exp_f32_e32 v58, v60
	v_exp_f32_e32 v59, v61
	v_exp_f32_e32 v60, v62
	v_exp_f32_e32 v61, v63
	s_waitcnt vmcnt(0)
	s_barrier
	v_mfma_f32_32x32x16_bf16 v[0:15], v[124:127], v[48:51], v[0:15]
	v_add_f32_e64 v48, v54, v52
	v_add_f32_e64 v49, v55, v53
	v_add_u32_e32 v52, s4, v105
	v_add_u32_e32 v105, v52, v107
	v_add_u32_e32 v118, v52, v106
	v_add_u32_e32 v103, v52, v103
	v_add_u32_e32 v119, v52, v101
	ds_read_b128 v[64:67], v105
	ds_read_b128 v[68:71], v105 offset:4096
	ds_read_b128 v[72:75], v118
	ds_read_b128 v[76:79], v118 offset:4096
	ds_read_b128 v[106:109], v103
	ds_read_b128 v[110:113], v103 offset:4096
	ds_read_b128 v[98:101], v119
	ds_read_b128 v[114:117], v119 offset:4096
	v_add_f32_e64 v48, v58, v48
	v_add_f32_e64 v49, v59, v49
	v_cvt_pk_bf16_f32 v50, v58, v59
	v_add_f32_e64 v96, v60, v48
	v_add_f32_e64 v97, v61, v49
	v_cvt_pk_bf16_f32 v48, v56, v57
	v_cvt_pk_bf16_f32 v49, v54, v55
	v_cvt_pk_bf16_f32 v51, v60, v61
	s_nop 1
	v_mfma_f32_32x32x16_bf16 v[32:47], v[128:131], v[48:51], v[32:47]
	v_mfma_f32_32x32x16_bf16 v[0:15], v[132:135], v[48:51], v[0:15]
	s_waitcnt lgkmcnt(0)
; #define MFMA(a, b, c) __builtin_amdgcn_mfma_f32_32x32x16_bf16((a), (b), (c), 0, 0, 0)
; DI int otid() { int t = threadIdx.x; asm volatile("" : "+v"(t)); return t; }
; DI void softmax_tile(f32x16 (&S)[2], float& lsum) {
;     f2_t ps = {0.f, 0.f};
; #pragma unroll
;     for (int t = 0; t < 2; ++t)
; #pragma unroll
;         for (int e = 0; e < 16; e += 2) {
;             f2_t pv; pv.x = __builtin_amdgcn_exp2f(S[t][e]); pv.y = __builtin_amdgcn_exp2f(S[t][e + 1]);
;             S[t][e] = pv.x; S[t][e + 1] = pv.y;
;             ps += pv;
;         }
;     lsum += ps.x + ps.y;
; }
; DI void pv_tile(const f32x16 (&S)[2], f32x16 (&O)[2], const bf16x8 (&vf)[8]) {
; #pragma unroll
;     for (int s = 0; s < 4; ++s) {
;         const bf16x8 pf = pack8(S[s >> 1], s & 1);
; #pragma unroll
;         for (int dt = 0; dt < 2; ++dt) O[dt] = MFMA(vf[2 * s + dt], pf, O[dt]);
;     }
; }
; template <int KIND>
; DI void attn_unit(const Params& p, int l, int b, int head, int qt, int qcol, int kcol, int vfeat, int gcol, int mixcol,
;                   int t1, int n1, int t2, int n2, char* smem) {
;     ...
;             } else {
;                 f32x16 S[2];
; #pragma unroll
;                 for (int t = 0; t < 2; ++t) S[t] = MFMA(kf[t], qf[0], cz);
; #pragma unroll
;                 for (int s = 1; s < 4; ++s)
; #pragma unroll
;                     for (int t = 0; t < 2; ++t) S[t] = MFMA(kf[2 * s + t], qf[s], S[t]);
;                 LOAD_VF();
;                 if (KIND == 2 && tile < 32) {
;                     const char* brow = smem + ATT_BIAS + (tile - nrow + 7) * 128;
; #pragma unroll
;                     for (int t = 0; t < 2; ++t)
; #pragma unroll
;                         for (int e = 0; e < 16; ++e) S[t][e] += *(const float*)(brow + bcol[t][e]);
;                 }
;                 softmax_tile(S, l0);
;                 pv_tile(S, O0, vf);
;             }
;     ...
;         }
;     }
;     l0 = xsum32(l0);
;     const float inv0 = 1.f / l0;
;     const int tid_e = otid();
;     const size_t qrow_e = (size_t)b * TPB + qt * 128 + 32 * (tid_e >> 6) + (tid_e & 31);
;     bf16_t* orow = p.hmix + ((size_t)(mixcol >> 5) * NTOK + qrow_e) * 32;
;     const bf16_t* grow = p.qkv + ((size_t)(gcol >> 6) * NTOK + qrow_e) * 64;
	v_mfma_f32_32x32x16_bf16 v[48:63], v[64:67], v[92:95], v[16:31]
	v_mfma_f32_32x32x16_bf16 v[16:31], v[68:71], v[92:95], v[16:31]
	v_mfma_f32_32x32x16_bf16 v[48:63], v[72:75], v[88:91], v[48:63]
	v_mfma_f32_32x32x16_bf16 v[16:31], v[76:79], v[88:91], v[16:31]
	v_mfma_f32_32x32x16_bf16 v[48:63], v[106:109], v[84:87], v[48:63]
	v_mfma_f32_32x32x16_bf16 v[16:31], v[110:113], v[84:87], v[16:31]
	v_mfma_f32_32x32x16_bf16 v[48:63], v[98:101], v[80:83], v[48:63]
	v_mfma_f32_32x32x16_bf16 v[16:31], v[114:117], v[80:83], v[16:31]
	ds_read_b128 v[92:95], v105 offset:8192
	ds_read_b128 v[76:79], v105 offset:12288
	ds_read_b128 v[88:91], v118 offset:8192
	ds_read_b128 v[72:75], v118 offset:12288
	ds_read_b128 v[84:87], v103 offset:8192
	ds_read_b128 v[68:71], v103 offset:12288
	ds_read_b128 v[80:83], v119 offset:8192
	ds_read_b128 v[64:67], v119 offset:12288
	s_nop 2
	v_exp_f32_e32 v98, v48
	v_exp_f32_e32 v99, v49
	v_exp_f32_e32 v50, v50
	v_exp_f32_e32 v51, v51
	v_exp_f32_e32 v52, v52
	v_exp_f32_e32 v53, v53
	v_exp_f32_e32 v54, v54
	v_exp_f32_e32 v55, v55
	v_add_f32_e64 v48, v98, 0
	v_add_f32_e64 v49, v99, 0
	v_exp_f32_e32 v56, v56
	v_exp_f32_e32 v57, v57
	v_add_f32_e64 v48, v50, v48
	v_add_f32_e64 v49, v51, v49
	v_mov_b32_e32 v103, v200
	v_add_f32_e64 v48, v52, v48
	v_add_f32_e64 v49, v53, v49
	s_add_u32 s4, s29, s6
	v_add_f32_e64 v48, v54, v48
	v_add_f32_e64 v49, v55, v49
	s_addc_u32 s5, s7, 0
	v_add_f32_e64 v100, v56, v48
	v_add_f32_e64 v101, v57, v49
	v_ashrrev_i32_e32 v48, 1, v103
	v_and_b32_e32 v48, 0xffffffe0, v48
	v_ashrrev_i32_e32 v49, 31, v48
	v_and_or_b32 v106, v103, 31, s4
	v_mov_b32_e32 v107, s5
	s_lshr_b32 s4, s9, 6
	v_lshl_add_u64 v[106:107], v[106:107], 0, v[48:49]
	s_mulk_i32 s4, 0x4800
	s_mov_b32 s5, s75
	v_lshl_add_u64 v[48:49], v[106:107], 0, s[4:5]
	v_lshlrev_b64 v[48:49], 7, v[48:49]
	v_lshl_add_u64 v[48:49], s[40:41], 0, v[48:49]
	v_lshlrev_b32_e32 v192, 3, v102
	v_lshl_add_u64 v[48:49], v[48:49], 0, v[192:193]
	global_load_dwordx2 v[102:103], v[48:49], off
	v_exp_f32_e32 v58, v58
	v_exp_f32_e32 v59, v59
	v_exp_f32_e32 v60, v60
	v_exp_f32_e32 v61, v61
	v_exp_f32_e32 v62, v62
	v_exp_f32_e32 v63, v63
	v_exp_f32_e32 v114, v28
	v_exp_f32_e32 v115, v29
	v_exp_f32_e32 v116, v30
	v_exp_f32_e32 v117, v31
	v_cvt_pk_bf16_f32 v28, v98, v99
	v_cvt_pk_bf16_f32 v29, v50, v51
	v_cvt_pk_bf16_f32 v30, v52, v53
	v_cvt_pk_bf16_f32 v31, v54, v55
	v_exp_f32_e32 v16, v16
	v_exp_f32_e32 v17, v17
	s_waitcnt lgkmcnt(0)
	v_mfma_f32_32x32x16_bf16 v[32:47], v[92:95], v[28:31], v[32:47]
	v_add_f32_e64 v100, v58, v100
	v_add_f32_e64 v101, v59, v101
	v_exp_f32_e32 v18, v18
	v_exp_f32_e32 v19, v19
	v_add_f32_e64 v100, v60, v100
	v_add_f32_e64 v101, v61, v101
	v_exp_f32_e32 v108, v20
	v_exp_f32_e32 v109, v21
	v_add_f32_e64 v100, v62, v100
	v_add_f32_e64 v101, v63, v101
	v_exp_f32_e32 v110, v22
	v_exp_f32_e32 v111, v23
	v_add_f32_e64 v20, v16, v100
	v_add_f32_e64 v21, v17, v101
	v_exp_f32_e32 v100, v24
	v_exp_f32_e32 v101, v25
	v_add_f32_e64 v20, v18, v20
	v_add_f32_e64 v21, v19, v21
	v_exp_f32_e32 v112, v26
	v_exp_f32_e32 v113, v27
	v_add_f32_e64 v20, v108, v20
	v_add_f32_e64 v21, v109, v21
	v_cvt_pk_bf16_f32 v24, v56, v57
	v_add_f32_e64 v20, v110, v20
	v_add_f32_e64 v21, v111, v21
	v_cvt_pk_bf16_f32 v25, v58, v59
	v_cvt_pk_bf16_f32 v26, v60, v61
	v_cvt_pk_bf16_f32 v27, v62, v63
	v_add_f32_e64 v20, v100, v20
	v_add_f32_e64 v21, v101, v21
	v_mov_b32_e32 v22, v96
	v_mfma_f32_32x32x16_bf16 v[32:47], v[88:91], v[24:27], v[32:47]
	v_add_f32_e64 v20, v112, v20
	v_add_f32_e64 v21, v113, v21
	s_lshr_b32 s6, s8, 5
	v_add_f32_e64 v20, v114, v20
	v_add_f32_e64 v21, v115, v21
	s_mulk_i32 s6, 0x4800
	v_add_f32_e64 v20, v116, v20
	v_add_f32_e64 v21, v117, v21
	s_ashr_i32 s7, s6, 31
	v_mov_b32_e32 v23, v20
	v_mov_b32_e32 v20, v97
	v_add_f32_e64 v20, v22, v20
	v_add_f32_e64 v21, v23, v21
	v_cvt_pk_bf16_f32 v22, v108, v109
	v_add_f32_e32 v20, v104, v20
	v_add_f32_e32 v50, v20, v21
	v_cvt_pk_bf16_f32 v20, v16, v17
	v_cvt_pk_bf16_f32 v21, v18, v19
	v_cvt_pk_bf16_f32 v23, v110, v111
	v_mov_b32_e32 v18, v50
	s_nop 1
	v_permlane32_swap_b32_e32 v50, v18
	v_mfma_f32_32x32x16_bf16 v[32:47], v[84:87], v[20:23], v[32:47]
	v_add_f32_e32 v50, v50, v18
	v_div_scale_f32 v51, s[4:5], v50, v50, 1.0
	v_rcp_f32_e32 v52, v51
	v_cvt_pk_bf16_f32 v16, v100, v101
	v_cvt_pk_bf16_f32 v17, v112, v113
	v_cvt_pk_bf16_f32 v18, v114, v115
	v_cvt_pk_bf16_f32 v19, v116, v117
	v_fma_f32 v53, -v51, v52, 1.0
	v_fmac_f32_e32 v52, v53, v52
	v_mfma_f32_32x32x16_bf16 v[32:47], v[80:83], v[16:19], v[32:47]
	v_div_scale_f32 v53, vcc, 1.0, v50, 1.0
	v_mul_f32_e32 v54, v53, v52
	v_fma_f32 v55, -v51, v54, v53
	v_fmac_f32_e32 v54, v55, v52
	s_load_dwordx2 s[4:5], s[0:1], 0xb8
	v_fma_f32 v51, -v51, v54, v53
	v_div_fmas_f32 v51, v51, v52, v54
	v_div_fixup_f32 v50, v51, v50, 1.0
	v_lshl_add_u64 v[52:53], v[106:107], 0, s[6:7]
	v_lshlrev_b64 v[52:53], 6, v[52:53]
	s_waitcnt vmcnt(0)
; DI unsigned pk2(float a, float b) { f2_t v = {a, b}; bf2_t r = __builtin_convertvector(v, bf2_t); return __builtin_bit_cast(unsigned, r); }
; DI float bf2f(bf16_t v) { return __uint_as_float(((unsigned)v) << 16); }
; template <int KIND>
; DI void attn_unit(const Params& p, int l, int b, int head, int qt, int qcol, int kcol, int vfeat, int gcol, int mixcol,
;                   int t1, int n1, int t2, int n2, char* smem) {
;     ...
;     } else {
; #pragma unroll
;         for (int t = 0; t < 2; ++t)
; #pragma unroll
;             for (int q = 0; q < 4; ++q) {
;                 const int f = 32 * t + 8 * q + 4 * h;
;                 const uint2 gg = *(const uint2*)(grow + f);
;                 const float g0 = bf2f((bf16_t)(gg.x & 0xffff)), g1 = bf2f((bf16_t)(gg.x >> 16)), g2 = bf2f((bf16_t)(gg.y & 0xffff)), g3 = bf2f((bf16_t)(gg.y >> 16));
;                 uint2 o;
;                 o.x = pk2(O0[t][4 * q + 0] * inv0 * g0, O0[t][4 * q + 1] * inv0 * g1);
;                 o.y = pk2(O0[t][4 * q + 2] * inv0 * g2, O0[t][4 * q + 3] * inv0 * g3);
;                 *(uint2*)(orow + (size_t)t * NTOK * 32 + 8 * q + 4 * h) = o;
;             }
;     }
	v_lshlrev_b32_e32 v54, 16, v102
	v_and_b32_e32 v55, 0xffff0000, v102
	v_lshlrev_b32_e32 v56, 16, v103
	v_and_b32_e32 v57, 0xffff0000, v103
	v_pk_mul_f32 v[32:33], v[32:33], v[50:51] op_sel_hi:[1,0]
	v_pk_mul_f32 v[34:35], v[34:35], v[50:51] op_sel_hi:[1,0]
	s_waitcnt lgkmcnt(0)
	v_lshl_add_u64 v[52:53], s[4:5], 0, v[52:53]
	v_pk_mul_f32 v[32:33], v[32:33], v[54:55]
	v_pk_mul_f32 v[34:35], v[34:35], v[56:57]
	v_lshl_add_u64 v[52:53], v[52:53], 0, v[192:193]
	v_cvt_pk_bf16_f32 v32, v32, v33
	v_cvt_pk_bf16_f32 v33, v34, v35
	global_store_dwordx2 v[52:53], v[32:33], off
	global_load_dwordx2 v[32:33], v[48:49], off offset:16
	v_mfma_f32_32x32x16_bf16 v[0:15], v[76:79], v[28:31], v[0:15]
	v_mul_f32_e64 v28, v36, v50
	v_mul_f32_e64 v29, v37, v50
	v_mul_f32_e64 v30, v38, v50
	v_mul_f32_e64 v31, v39, v50
	s_mov_b32 s4, 0x120000
	s_waitcnt vmcnt(0)
	v_lshlrev_b32_e32 v34, 16, v32
	v_and_b32_e32 v35, 0xffff0000, v32
	v_lshlrev_b32_e32 v32, 16, v33
	v_and_b32_e32 v33, 0xffff0000, v33
	v_pk_mul_f32 v[28:29], v[28:29], v[34:35]
	v_pk_mul_f32 v[30:31], v[30:31], v[32:33]
	v_cvt_pk_bf16_f32 v28, v28, v29
	v_cvt_pk_bf16_f32 v29, v30, v31
	global_store_dwordx2 v[52:53], v[28:29], off offset:16
	global_load_dwordx2 v[28:29], v[48:49], off offset:32
	v_mfma_f32_32x32x16_bf16 v[0:15], v[72:75], v[24:27], v[0:15]
	v_mul_f32_e64 v24, v40, v50
	v_mul_f32_e64 v25, v41, v50
	v_mul_f32_e64 v26, v42, v50
	v_mul_f32_e64 v27, v43, v50
	s_waitcnt vmcnt(0)
	v_lshlrev_b32_e32 v30, 16, v28
	v_and_b32_e32 v31, 0xffff0000, v28
	v_lshlrev_b32_e32 v28, 16, v29
	v_and_b32_e32 v29, 0xffff0000, v29
	v_pk_mul_f32 v[24:25], v[24:25], v[30:31]
	v_pk_mul_f32 v[26:27], v[26:27], v[28:29]
	v_cvt_pk_bf16_f32 v24, v24, v25
	v_cvt_pk_bf16_f32 v25, v26, v27
	global_store_dwordx2 v[52:53], v[24:25], off offset:32
	global_load_dwordx2 v[24:25], v[48:49], off offset:48
	v_mfma_f32_32x32x16_bf16 v[0:15], v[68:71], v[20:23], v[0:15]
	v_mul_f32_e64 v20, v44, v50
	v_mul_f32_e64 v21, v45, v50
	v_mul_f32_e64 v22, v46, v50
	v_mul_f32_e64 v23, v47, v50
	s_waitcnt vmcnt(0)
	v_lshlrev_b32_e32 v26, 16, v24
	v_and_b32_e32 v27, 0xffff0000, v24
	v_lshlrev_b32_e32 v24, 16, v25
	v_and_b32_e32 v25, 0xffff0000, v25
	v_pk_mul_f32 v[20:21], v[20:21], v[26:27]
	v_pk_mul_f32 v[22:23], v[22:23], v[24:25]
	v_cvt_pk_bf16_f32 v20, v20, v21
	v_cvt_pk_bf16_f32 v21, v22, v23
	global_store_dwordx2 v[52:53], v[20:21], off offset:48
	global_load_dwordx2 v[20:21], v[48:49], off offset:64
	v_mfma_f32_32x32x16_bf16 v[0:15], v[64:67], v[16:19], v[0:15]
	v_add_co_u32_e32 v22, vcc, s4, v52
	s_mov_b64 s[4:5], 0
	s_nop 0
	v_addc_co_u32_e32 v23, vcc, 0, v53, vcc
	s_waitcnt vmcnt(0)
	v_lshlrev_b32_e32 v16, 16, v20
	s_nop 5
	v_pk_mul_f32 v[0:1], v[0:1], v[50:51] op_sel_hi:[1,0]
	v_pk_mul_f32 v[2:3], v[2:3], v[50:51] op_sel_hi:[1,0]
	v_and_b32_e32 v17, 0xffff0000, v20
	v_lshlrev_b32_e32 v18, 16, v21
	v_and_b32_e32 v19, 0xffff0000, v21
	v_pk_mul_f32 v[0:1], v[0:1], v[16:17]
	v_pk_mul_f32 v[2:3], v[2:3], v[18:19]
	v_cvt_pk_bf16_f32 v0, v0, v1
	v_cvt_pk_bf16_f32 v1, v2, v3
	global_store_dwordx2 v[22:23], v[0:1], off
	global_load_dwordx2 v[0:1], v[48:49], off offset:80
	v_pk_mul_f32 v[2:3], v[4:5], v[50:51] op_sel_hi:[1,0]
	v_pk_mul_f32 v[4:5], v[6:7], v[50:51] op_sel_hi:[1,0]
	s_waitcnt vmcnt(0)
	v_lshlrev_b32_e32 v6, 16, v0
	v_and_b32_e32 v7, 0xffff0000, v0
	v_lshlrev_b32_e32 v0, 16, v1
	v_and_b32_e32 v1, 0xffff0000, v1
	v_pk_mul_f32 v[2:3], v[2:3], v[6:7]
	v_pk_mul_f32 v[0:1], v[4:5], v[0:1]
	v_cvt_pk_bf16_f32 v2, v2, v3
	v_cvt_pk_bf16_f32 v3, v0, v1
	global_store_dwordx2 v[22:23], v[2:3], off offset:16
	global_load_dwordx2 v[0:1], v[48:49], off offset:96
	v_pk_mul_f32 v[2:3], v[8:9], v[50:51] op_sel_hi:[1,0]
	v_pk_mul_f32 v[4:5], v[10:11], v[50:51] op_sel_hi:[1,0]
	s_waitcnt vmcnt(0)
	v_lshlrev_b32_e32 v6, 16, v0
	v_and_b32_e32 v7, 0xffff0000, v0
	v_lshlrev_b32_e32 v0, 16, v1
	v_and_b32_e32 v1, 0xffff0000, v1
	v_pk_mul_f32 v[2:3], v[2:3], v[6:7]
	v_pk_mul_f32 v[0:1], v[4:5], v[0:1]
	v_cvt_pk_bf16_f32 v2, v2, v3
	v_cvt_pk_bf16_f32 v3, v0, v1
	global_store_dwordx2 v[22:23], v[2:3], off offset:32
	global_load_dwordx2 v[0:1], v[48:49], off offset:112
	v_pk_mul_f32 v[2:3], v[12:13], v[50:51] op_sel_hi:[1,0]
	v_pk_mul_f32 v[4:5], v[14:15], v[50:51] op_sel_hi:[1,0]
	s_waitcnt vmcnt(0)
	v_lshlrev_b32_e32 v6, 16, v0
	v_and_b32_e32 v7, 0xffff0000, v0
	v_lshlrev_b32_e32 v0, 16, v1
	v_and_b32_e32 v1, 0xffff0000, v1
	v_pk_mul_f32 v[2:3], v[2:3], v[6:7]
	v_pk_mul_f32 v[0:1], v[4:5], v[0:1]
	v_cvt_pk_bf16_f32 v2, v2, v3
	v_cvt_pk_bf16_f32 v3, v0, v1
	global_store_dwordx2 v[22:23], v[2:3], off offset:48
	s_branch .LBB0_85

; DI int otid() { int t = threadIdx.x; asm volatile("" : "+v"(t)); return t; }
; template <bool VMODE, int TJ>
; DI void gemm_mainloop(const bf16_t* __restrict__ W, const bf16_t* __restrict__ X, int NW, char* smem, f32x16 (&acc)[2][TJ]) {
;     constexpr int XROWS = 64 * TJ, STAGE = (128 + XROWS) * 64, NPW = 2 + TJ;
;     const int tid = otid(), lane = tid & 63, wave = tid >> 6, r = lane & 31, h = lane >> 5, wf = wave & 1, wt = wave >> 1;
;     const int goff = (16 * wave + (lane >> 2)) * 32 + (((lane & 3) ^ (lane >> 4)) << 3);
;     const bf16_t* wp = W + goff;
;     const bf16_t* xp = X + goff;
;     const size_t wks = (size_t)NW * 32, xks = (size_t)NTOK * 32;
;     char* ld = smem + tid * 16;
;     ...
;     const int xr = (r >> 2) & 3;
;     const int fo0 = r * 64 + (((0 + h) ^ xr) << 4), fo1 = r * 64 + (((2 + h) ^ xr) << 4);
;     __syncthreads();
; DI void inproj_phase(const Params& p, int l, char* smem) {
;     ...
;         const int n0 = nt * 128;
;         const bf16_t* W = p.wtin + (size_t)l * INW * D + (size_t)n0 * 32;
;         const bf16_t* X = p.hmix + (size_t)mtile * 256 * 32;
;         f32x16 acc[2][4];
;         zero_acc<4>(acc);
;         int vf0 = -1;
;         if (n0 >= 512 && n0 < 768) vf0 = n0 - 512;
;         else if (n0 >= 1536 && n0 < 1664) vf0 = 256 + (n0 - 1536);
;         else if (n0 >= 2816 && n0 < 3200) vf0 = 384 + (n0 - 2816);
;         if (vf0 >= 0) { gemm_mainloop<true, 4>(W, X, INW, smem, acc); epi_v(p, mtile, vf0, acc, smem); }
.LBB0_200:
	s_load_dwordx2 s[4:5], s[0:1], 0xd0
	s_load_dwordx2 s[6:7], s[0:1], 0xb8
	s_mul_hi_i32 s47, s50, 0x38e38e39
	s_waitcnt lgkmcnt(0)
	s_add_u32 s8, s4, s63
	s_addc_u32 s9, s5, s62
	s_ashr_i32 s59, s58, 31
	s_lshl_b64 s[4:5], s[58:59], 6
	s_add_u32 s52, s8, s4
	s_addc_u32 s53, s9, s5
	s_ashr_i32 s51, s50, 31
	s_lshl_b64 s[4:5], s[50:51], 14
	s_add_u32 s56, s6, s4
	s_addc_u32 s57, s7, s5
	s_mov_b64 s[4:5], -1
	s_cmp_lt_i32 s46, 0
	s_cbranch_scc0 .LBB0_287
	v_mov_b32_e32 v4, v200
	s_movk_i32 s4, 0xffe0
	v_bfe_u32 v1, v4, 4, 2
	v_bitop3_b32 v1, v1, v4, 3 bitop3:0x78
	v_lshlrev_b32_e32 v0, 3, v4
	v_lshlrev_b32_e32 v1, 3, v1
	v_and_or_b32 v0, v0, s4, v1
	v_bfe_u32 v5, v4, 5, 1
	v_ashrrev_i32_e32 v1, 31, v0
	v_lshl_add_u32 v130, v4, 4, 32
	v_bfe_u32 v7, v4, 2, 2
	v_lshlrev_b64 v[128:129], 1, v[0:1]
	v_bitop3_b32 v9, v5, v7, 2 bitop3:0x36
	v_readfirstlane_b32 s4, v130
	v_add_u32_e32 v7, 0x1000, v130
	v_lshl_add_u64 v[0:1], s[52:53], 0, v[128:129]
	v_lshrrev_b32_e32 v6, 2, v4
	s_mov_b32 m0, s4
	v_readfirstlane_b32 s4, v7
	v_lshlrev_b32_e32 v8, 6, v4
	v_bitop3_b32 v6, v5, v6, 3 bitop3:0x78
	s_barrier
	global_load_lds_dwordx4 v[0:1], off
	v_lshl_add_u64 v[4:5], v[0:1], 0, s[26:27]
	s_mov_b32 m0, s4
	v_add_u32_e32 v7, 0x3000, v130
	global_load_lds_dwordx4 v[4:5], off
	v_add_u32_e32 v4, 0x2000, v130
	v_lshl_add_u64 v[2:3], s[56:57], 0, v[128:129]
	v_readfirstlane_b32 s4, v4
	s_mov_b32 m0, s4
	v_readfirstlane_b32 s4, v7
	v_add_u32_e32 v7, 0x4000, v130
	global_load_lds_dwordx4 v[2:3], off
	v_lshl_add_u64 v[4:5], v[2:3], 0, s[26:27]
	s_mov_b32 m0, s4
	v_readfirstlane_b32 s4, v7
	v_add_u32_e32 v7, 0x5000, v130
	global_load_lds_dwordx4 v[4:5], off
	v_lshl_add_u64 v[4:5], v[2:3], 0, s[16:17]
	s_mov_b32 m0, s4
	v_readfirstlane_b32 s4, v7
	global_load_lds_dwordx4 v[4:5], off
	v_lshl_add_u64 v[4:5], v[2:3], 0, s[90:91]
	s_mov_b32 m0, s4
	s_mov_b64 s[4:5], 0x38000
	global_load_lds_dwordx4 v[4:5], off
	v_and_b32_e32 v10, 0x7c0, v8
	v_lshl_add_u64 v[4:5], v[0:1], 0, s[4:5]
	s_mov_b64 s[4:5], 0x120000
	v_add_u32_e32 v11, 0x6000, v130
	v_lshl_or_b32 v131, v6, 4, v10
	v_lshl_add_u64 v[6:7], v[2:3], 0, s[4:5]
	v_readfirstlane_b32 s4, v11
	s_mov_b32 m0, s4
	s_mov_b64 s[4:5], 0x39000
	global_load_lds_dwordx4 v[4:5], off
	v_add_u32_e32 v4, 0x7000, v130
	v_lshl_add_u64 v[0:1], v[0:1], 0, s[4:5]
	v_readfirstlane_b32 s4, v4
	s_mov_b32 m0, s4
	v_add_u32_e32 v4, 0x9000, v130
	global_load_lds_dwordx4 v[0:1], off
	v_add_u32_e32 v0, 0x8000, v130
	s_mov_b32 s8, 2
	v_readfirstlane_b32 s4, v0
	s_mov_b32 m0, s4
	s_mov_b64 s[4:5], 0x121000
	v_lshl_add_u64 v[0:1], v[2:3], 0, s[4:5]
	v_readfirstlane_b32 s4, v4
	global_load_lds_dwordx4 v[6:7], off
	s_mov_b32 m0, s4
	s_mov_b64 s[4:5], 0x122000
	v_add_u32_e32 v4, 0xa000, v130
	global_load_lds_dwordx4 v[0:1], off
	v_lshl_add_u64 v[0:1], v[2:3], 0, s[4:5]
	v_readfirstlane_b32 s4, v4
	s_mov_b32 m0, s4
	s_mov_b64 s[4:5], 0x123000
	global_load_lds_dwordx4 v[0:1], off
	v_lshl_add_u64 v[0:1], v[2:3], 0, s[4:5]
	v_add_u32_e32 v2, 0xb000, v130
	v_lshl_or_b32 v132, v9, 4, v10
	v_readfirstlane_b32 s4, v2
	s_mov_b32 m0, s4
	v_and_b32_e32 v134, 0x1000, v8
	global_load_lds_dwordx4 v[0:1], off
	v_mov_b32_e32 v0, 0
	v_and_b32_e32 v133, 0xffffe000, v8
	s_mov_b32 s28, 0
	s_mov_b32 s9, 30
	s_mov_b64 s[4:5], s[52:53]
	s_mov_b64 s[6:7], s[56:57]
	v_mov_b32_e32 v1, v0
	v_mov_b32_e32 v2, v0
	v_mov_b32_e32 v3, v0
	v_mov_b32_e32 v4, v0
	v_mov_b32_e32 v5, v0
	v_mov_b32_e32 v6, v0
	v_mov_b32_e32 v7, v0
	v_mov_b32_e32 v8, v0
	v_mov_b32_e32 v9, v0
	v_mov_b32_e32 v10, v0
	v_mov_b32_e32 v11, v0
	v_mov_b32_e32 v12, v0
	v_mov_b32_e32 v13, v0
	v_mov_b32_e32 v14, v0
	v_mov_b32_e32 v15, v0
	v_mov_b32_e32 v32, v0
	v_mov_b32_e32 v33, v0
	v_mov_b32_e32 v34, v0
	v_mov_b32_e32 v35, v0
	v_mov_b32_e32 v36, v0
	v_mov_b32_e32 v37, v0
	v_mov_b32_e32 v38, v0
	v_mov_b32_e32 v39, v0
	v_mov_b32_e32 v40, v0
	v_mov_b32_e32 v41, v0
	v_mov_b32_e32 v42, v0
	v_mov_b32_e32 v43, v0
	v_mov_b32_e32 v44, v0
	v_mov_b32_e32 v45, v0
	v_mov_b32_e32 v46, v0
	v_mov_b32_e32 v47, v0
	v_mov_b32_e32 v64, v0
	v_mov_b32_e32 v65, v0
	v_mov_b32_e32 v66, v0
	v_mov_b32_e32 v67, v0
	v_mov_b32_e32 v68, v0
	v_mov_b32_e32 v69, v0
	v_mov_b32_e32 v70, v0
	v_mov_b32_e32 v71, v0
	v_mov_b32_e32 v72, v0
	v_mov_b32_e32 v73, v0
	v_mov_b32_e32 v74, v0
	v_mov_b32_e32 v75, v0
	v_mov_b32_e32 v76, v0
	v_mov_b32_e32 v77, v0
	v_mov_b32_e32 v78, v0
	v_mov_b32_e32 v79, v0
	v_mov_b32_e32 v96, v0
	v_mov_b32_e32 v97, v0
	v_mov_b32_e32 v98, v0
	v_mov_b32_e32 v99, v0
	v_mov_b32_e32 v100, v0
	v_mov_b32_e32 v101, v0
	v_mov_b32_e32 v102, v0
	v_mov_b32_e32 v103, v0
	v_mov_b32_e32 v104, v0
	v_mov_b32_e32 v105, v0
	v_mov_b32_e32 v106, v0
	v_mov_b32_e32 v107, v0
	v_mov_b32_e32 v108, v0
	v_mov_b32_e32 v109, v0
	v_mov_b32_e32 v110, v0
	v_mov_b32_e32 v111, v0
	v_mov_b32_e32 v16, v0
	v_mov_b32_e32 v17, v0
	v_mov_b32_e32 v18, v0
	v_mov_b32_e32 v19, v0
	v_mov_b32_e32 v20, v0
	v_mov_b32_e32 v21, v0
	v_mov_b32_e32 v22, v0
	v_mov_b32_e32 v23, v0
	v_mov_b32_e32 v24, v0
	v_mov_b32_e32 v25, v0
	v_mov_b32_e32 v26, v0
	v_mov_b32_e32 v27, v0
	v_mov_b32_e32 v28, v0
	v_mov_b32_e32 v29, v0
	v_mov_b32_e32 v30, v0
	v_mov_b32_e32 v31, v0
	v_mov_b32_e32 v48, v0
	v_mov_b32_e32 v49, v0
	v_mov_b32_e32 v50, v0
	v_mov_b32_e32 v51, v0
	v_mov_b32_e32 v52, v0
	v_mov_b32_e32 v53, v0
	v_mov_b32_e32 v54, v0
	v_mov_b32_e32 v55, v0
	v_mov_b32_e32 v56, v0
	v_mov_b32_e32 v57, v0
	v_mov_b32_e32 v58, v0
	v_mov_b32_e32 v59, v0
	v_mov_b32_e32 v60, v0
	v_mov_b32_e32 v61, v0
	v_mov_b32_e32 v62, v0
	v_mov_b32_e32 v63, v0
	v_mov_b32_e32 v80, v0
	v_mov_b32_e32 v81, v0
	v_mov_b32_e32 v82, v0
	v_mov_b32_e32 v83, v0
	v_mov_b32_e32 v84, v0
	v_mov_b32_e32 v85, v0
	v_mov_b32_e32 v86, v0
	v_mov_b32_e32 v87, v0
	v_mov_b32_e32 v88, v0
	v_mov_b32_e32 v89, v0
	v_mov_b32_e32 v90, v0
	v_mov_b32_e32 v91, v0
	v_mov_b32_e32 v92, v0
	v_mov_b32_e32 v93, v0
	v_mov_b32_e32 v94, v0
	v_mov_b32_e32 v95, v0
	v_mov_b32_e32 v112, v0
	v_mov_b32_e32 v113, v0
	v_mov_b32_e32 v114, v0
	v_mov_b32_e32 v115, v0
	v_mov_b32_e32 v116, v0
	v_mov_b32_e32 v117, v0
	v_mov_b32_e32 v118, v0
	v_mov_b32_e32 v119, v0
	v_mov_b32_e32 v120, v0
	v_mov_b32_e32 v121, v0
	v_mov_b32_e32 v122, v0
	v_mov_b32_e32 v123, v0
	v_mov_b32_e32 v124, v0
	v_mov_b32_e32 v125, v0
	v_mov_b32_e32 v126, v0
	v_mov_b32_e32 v127, v0
	v_readfirstlane_b32 s100, v130
	v_add_u32_e32 v170, 0x38000, v128
	v_add_u32_e32 v171, 0x39000, v128
	v_add_u32_e32 v172, 0x120000, v128
	v_add_u32_e32 v173, 0x121000, v128
	v_add_u32_e32 v174, 0x122000, v128
	v_add_u32_e32 v175, 0x123000, v128
; #define MFMA(a, b, c) __builtin_amdgcn_mfma_f32_32x32x16_bf16((a), (b), (c), 0, 0, 0)
; #define G_ISSUE(ks_, buf_) do { \
;     const bf16_t* wq_ = wp + (ks_) * wks; const bf16_t* xq_ = xp + (ks_) * xks; char* lb_ = ld + (buf_) * STAGE; \
;     dma16(wq_, lb_); dma16(wq_ + 2048, lb_ + 4096); \
;     _Pragma("unroll") for (int i_ = 0; i_ < TJ; ++i_) dma16(xq_ + i_ * 2048, lb_ + 8192 + i_ * 4096); } while (0)
; template <bool VMODE, int TJ>
; DI void gemm_mainloop(const bf16_t* __restrict__ W, const bf16_t* __restrict__ X, int NW, char* smem, f32x16 (&acc)[2][TJ]) {
;     ...
;         for (int ks = 0; ks < 32; ++ks) {
;             if (ks < 31) asm volatile("s_waitcnt vmcnt(6)" ::: "memory");
;             else asm volatile("s_waitcnt vmcnt(0)" ::: "memory");
;             __builtin_amdgcn_s_barrier();
;             const char* sw = smem + bc * STAGE + wf * 64 * 64;
;             const char* sx = smem + bc * STAGE + 8192 + wt * (32 * TJ) * 64;
;             bf16x8 fw[2], fx[TJ], gw[2], gx[TJ];
; #pragma unroll
;             for (int i = 0; i < 2; ++i) fw[i] = *(const bf16x8*)(sw + i * 32 * 64 + fo0);
; #pragma unroll
;             for (int j = 0; j < TJ; ++j) fx[j] = *(const bf16x8*)(sx + j * 32 * 64 + fo0);
;             __builtin_amdgcn_sched_barrier(0);
;             if (ks + 2 < 32) G_ISSUE(ks + 2, bn);
;             __builtin_amdgcn_sched_barrier(0);
; #pragma unroll
;             for (int i = 0; i < 2; ++i) gw[i] = *(const bf16x8*)(sw + i * 32 * 64 + fo1);
; #pragma unroll
;             for (int j = 0; j < TJ; ++j) gx[j] = *(const bf16x8*)(sx + j * 32 * 64 + fo1);
; #pragma unroll
;             for (int i = 0; i < 2; ++i)
; #pragma unroll
;                 for (int j = 0; j < TJ; ++j) acc[i][j] = VMODE ? MFMA(fx[j], fw[i], acc[i][j]) : MFMA(fw[i], fx[j], acc[i][j]);
; #pragma unroll
;             for (int i = 0; i < 2; ++i)
; #pragma unroll
;                 for (int j = 0; j < TJ; ++j) acc[i][j] = VMODE ? MFMA(gx[j], gw[i], acc[i][j]) : MFMA(gw[i], gx[j], acc[i][j]);
;             bc = (bc == 2) ? 0 : bc + 1; bn = (bn == 2) ? 0 : bn + 1;
;         }
.LBB0_202:
	s_mul_i32 s29, s28, 0x6000
	s_add_i32 s29, s29, 32
	v_add_u32_e32 v135, s29, v134
	v_add_u32_e32 v168, s29, v133
	v_add_u32_e32 v140, v135, v131
	v_add_u32_e32 v156, v168, v131
	s_waitcnt vmcnt(6)
	s_barrier
	ds_read_b128 v[136:139], v140
	ds_read_b128 v[140:143], v140 offset:2048
	ds_read_b128 v[144:147], v156 offset:8192
	ds_read_b128 v[148:151], v156 offset:10240
	ds_read_b128 v[152:155], v156 offset:12288
	ds_read_b128 v[156:159], v156 offset:14336
	s_mul_i32 s29, s8, 0x6000
	s_add_i32 s101, s29, s100
	s_add_i32 s29, s28, 1
	s_cmp_lg_u32 s28, 2
	s_cselect_b32 s28, s29, 0
	s_add_i32 s29, s8, 1
	s_cmp_lg_u32 s8, 2
	s_cselect_b32 s8, s29, 0
	s_add_i32 s9, s9, -1
	s_add_u32 s6, s6, 0x120000
	s_addc_u32 s7, s7, 0
	s_add_u32 s4, s4, 0x38000
	s_addc_u32 s5, s5, 0
	s_mov_b32 m0, s101
	s_waitcnt lgkmcnt(0)
	v_mfma_f32_32x32x16_bf16 v[112:127], v[136:139], v[144:147], v[112:127]
	global_load_lds_dwordx4 v170, s[4:5]
	s_add_u32 m0, s101, 0x1000
	v_add_u32_e32 v135, v135, v132
	v_add_u32_e32 v160, v168, v132
	v_mfma_f32_32x32x16_bf16 v[80:95], v[136:139], v[148:151], v[80:95]
	global_load_lds_dwordx4 v171, s[4:5]
	s_add_u32 m0, s101, 0x2000
	v_mfma_f32_32x32x16_bf16 v[48:63], v[136:139], v[152:155], v[48:63]
	global_load_lds_dwordx4 v172, s[6:7]
	s_add_u32 m0, s101, 0x3000
	v_mfma_f32_32x32x16_bf16 v[16:31], v[136:139], v[156:159], v[16:31]
	global_load_lds_dwordx4 v173, s[6:7]
	s_add_u32 m0, s101, 0x4000
	v_mfma_f32_32x32x16_bf16 v[96:111], v[140:143], v[144:147], v[96:111]
	global_load_lds_dwordx4 v174, s[6:7]
	s_add_u32 m0, s101, 0x5000
	v_mfma_f32_32x32x16_bf16 v[64:79], v[140:143], v[148:151], v[64:79]
	global_load_lds_dwordx4 v175, s[6:7]
	v_mfma_f32_32x32x16_bf16 v[32:47], v[140:143], v[152:155], v[32:47]
	v_mfma_f32_32x32x16_bf16 v[0:15], v[140:143], v[156:159], v[0:15]
	ds_read_b128 v[136:139], v135
	ds_read_b128 v[140:143], v160 offset:8192
	ds_read_b128 v[144:147], v135 offset:2048
	ds_read_b128 v[148:151], v160 offset:10240
	ds_read_b128 v[152:155], v160 offset:12288
	ds_read_b128 v[156:159], v160 offset:14336
	s_waitcnt lgkmcnt(0)
	v_mfma_f32_32x32x16_bf16 v[112:127], v[136:139], v[140:143], v[112:127]
	v_mfma_f32_32x32x16_bf16 v[80:95], v[136:139], v[148:151], v[80:95]
	v_mfma_f32_32x32x16_bf16 v[48:63], v[136:139], v[152:155], v[48:63]
	v_mfma_f32_32x32x16_bf16 v[16:31], v[136:139], v[156:159], v[16:31]
	v_mfma_f32_32x32x16_bf16 v[96:111], v[144:147], v[140:143], v[96:111]
	v_mfma_f32_32x32x16_bf16 v[64:79], v[144:147], v[148:151], v[64:79]
	v_mfma_f32_32x32x16_bf16 v[32:47], v[144:147], v[152:155], v[32:47]
	v_mfma_f32_32x32x16_bf16 v[0:15], v[144:147], v[156:159], v[0:15]
	s_cmp_lg_u32 s9, 0
	s_cbranch_scc1 .LBB0_202
	v_add_u32_e32 v154, 32, v134
	v_add_u32_e32 v133, 32, v133
	v_add_u32_e32 v155, v154, v131
	v_add_u32_e32 v156, v133, v131
	s_waitcnt vmcnt(6)
	s_barrier
	ds_read_b128 v[134:137], v155
	ds_read_b128 v[138:141], v155 offset:2048
	ds_read_b128 v[128:131], v156 offset:8192
	ds_read_b128 v[142:145], v156 offset:10240
	ds_read_b128 v[146:149], v156 offset:12288
	ds_read_b128 v[150:153], v156 offset:14336
	v_add_u32_e32 v160, v154, v132
	s_waitcnt lgkmcnt(0)
	v_mfma_f32_32x32x16_bf16 v[112:127], v[134:137], v[128:131], v[112:127]
	v_add_u32_e32 v161, v133, v132
	v_mfma_f32_32x32x16_bf16 v[96:111], v[138:141], v[128:131], v[96:111]
	ds_read_b128 v[128:131], v160
	v_mfma_f32_32x32x16_bf16 v[80:95], v[134:137], v[142:145], v[80:95]
	v_mfma_f32_32x32x16_bf16 v[48:63], v[134:137], v[146:149], v[48:63]
	v_mfma_f32_32x32x16_bf16 v[16:31], v[134:137], v[150:153], v[16:31]
	v_mfma_f32_32x32x16_bf16 v[64:79], v[138:141], v[142:145], v[64:79]
	v_mfma_f32_32x32x16_bf16 v[32:47], v[138:141], v[146:149], v[32:47]
	v_mfma_f32_32x32x16_bf16 v[0:15], v[138:141], v[150:153], v[0:15]
	ds_read_b128 v[132:135], v161 offset:8192
	ds_read_b128 v[136:139], v160 offset:2048
	ds_read_b128 v[140:143], v161 offset:10240
	ds_read_b128 v[144:147], v161 offset:12288
	ds_read_b128 v[148:151], v161 offset:14336
	s_waitcnt vmcnt(0)
	s_barrier
; #define MFMA(a, b, c) __builtin_amdgcn_mfma_f32_32x32x16_bf16((a), (b), (c), 0, 0, 0)
; template <bool VMODE, int TJ>
; DI void gemm_mainloop(const bf16_t* __restrict__ W, const bf16_t* __restrict__ X, int NW, char* smem, f32x16 (&acc)[2][TJ]) {
;     ...
;         for (int ks = 0; ks < 32; ++ks) {
;             if (ks < 31) asm volatile("s_waitcnt vmcnt(6)" ::: "memory");
;             else asm volatile("s_waitcnt vmcnt(0)" ::: "memory");
;             __builtin_amdgcn_s_barrier();
;             const char* sw = smem + bc * STAGE + wf * 64 * 64;
;             const char* sx = smem + bc * STAGE + 8192 + wt * (32 * TJ) * 64;
;             bf16x8 fw[2], fx[TJ], gw[2], gx[TJ];
; #pragma unroll
;             for (int i = 0; i < 2; ++i) fw[i] = *(const bf16x8*)(sw + i * 32 * 64 + fo0);
; #pragma unroll
;             for (int j = 0; j < TJ; ++j) fx[j] = *(const bf16x8*)(sx + j * 32 * 64 + fo0);
;             __builtin_amdgcn_sched_barrier(0);
;             if (ks + 2 < 32) G_ISSUE(ks + 2, bn);
;             __builtin_amdgcn_sched_barrier(0);
; #pragma unroll
;             for (int i = 0; i < 2; ++i) gw[i] = *(const bf16x8*)(sw + i * 32 * 64 + fo1);
; #pragma unroll
;             for (int j = 0; j < TJ; ++j) gx[j] = *(const bf16x8*)(sx + j * 32 * 64 + fo1);
; #pragma unroll
;             for (int i = 0; i < 2; ++i)
; #pragma unroll
;                 for (int j = 0; j < TJ; ++j) acc[i][j] = VMODE ? MFMA(fx[j], fw[i], acc[i][j]) : MFMA(fw[i], fx[j], acc[i][j]);
; #pragma unroll
;             for (int i = 0; i < 2; ++i)
; #pragma unroll
;                 for (int j = 0; j < TJ; ++j) acc[i][j] = VMODE ? MFMA(gx[j], gw[i], acc[i][j]) : MFMA(gw[i], gx[j], acc[i][j]);
;             bc = (bc == 2) ? 0 : bc + 1; bn = (bn == 2) ? 0 : bn + 1;
;         }
;     }
; DI void epi_inproj(const Params& p, int l, int mtile, int n0, f32x16 (&acc)[2][4], char* smem) {
;     ...
;     if (n0 < 256) { type = 2; nwt = p.dqn + l * 32; rope = true; }
;     else if (n0 < 512) { type = 2; nwt = p.dkn + l * 32; rope = true; }
;     else if (n0 < 1024) { type = 1; }
;     else if (n0 < 1408) { type = 3; nwt = p.gqn + l * 64; rope = true; }
;     else if (n0 < 1536) { type = 3; nwt = p.gkn + l * 64; rope = true; }
;     else if (n0 < 2048) { type = 1; }
;     else if (n0 < 2432) { type = 3; nwt = p.nqn + l * 64; }
;     else if (n0 < 2816) { type = 3; nwt = p.nkn + l * 64; }
;     else { type = 1; }
	s_waitcnt lgkmcnt(0)
	v_mfma_f32_32x32x16_bf16 v[112:127], v[128:131], v[132:135], v[112:127]
	v_mfma_f32_32x32x16_bf16 v[80:95], v[128:131], v[140:143], v[80:95]
	v_mfma_f32_32x32x16_bf16 v[48:63], v[128:131], v[144:147], v[48:63]
	v_mfma_f32_32x32x16_bf16 v[16:31], v[128:131], v[148:151], v[16:31]
	v_mfma_f32_32x32x16_bf16 v[96:111], v[136:139], v[132:135], v[96:111]
	v_mfma_f32_32x32x16_bf16 v[64:79], v[136:139], v[140:143], v[64:79]
	v_mfma_f32_32x32x16_bf16 v[32:47], v[136:139], v[144:147], v[32:47]
	ds_read_b128 v[128:131], v155 offset:24576
	ds_read_b128 v[132:135], v155 offset:26624
	ds_read_b128 v[140:143], v156 offset:32768
	ds_read_b128 v[144:147], v156 offset:34816
	ds_read_b128 v[152:155], v156 offset:36864
	ds_read_b128 v[156:159], v156 offset:38912
	v_mfma_f32_32x32x16_bf16 v[0:15], v[136:139], v[148:151], v[0:15]
	s_waitcnt lgkmcnt(0)
	v_mfma_f32_32x32x16_bf16 v[112:127], v[128:131], v[140:143], v[112:127]
	s_cmp_lt_i32 s99, 2
	s_cselect_b64 s[40:41], -1, 0
	s_cmp_gt_i32 s99, 1
	s_mov_b64 s[6:7], -1
	v_mfma_f32_32x32x16_bf16 v[80:95], v[128:131], v[144:147], v[80:95]
	v_mfma_f32_32x32x16_bf16 v[48:63], v[128:131], v[152:155], v[48:63]
	v_mfma_f32_32x32x16_bf16 v[16:31], v[128:131], v[156:159], v[16:31]
	v_mfma_f32_32x32x16_bf16 v[96:111], v[132:135], v[140:143], v[96:111]
	v_mfma_f32_32x32x16_bf16 v[64:79], v[132:135], v[144:147], v[64:79]
	v_mfma_f32_32x32x16_bf16 v[32:47], v[132:135], v[152:155], v[32:47]
	v_mfma_f32_32x32x16_bf16 v[0:15], v[132:135], v[156:159], v[0:15]
	ds_read_b128 v[128:131], v160 offset:24576
	ds_read_b128 v[132:135], v161 offset:32768
	ds_read_b128 v[136:139], v160 offset:26624
	ds_read_b128 v[140:143], v161 offset:34816
	ds_read_b128 v[144:147], v161 offset:36864
	ds_read_b128 v[148:151], v161 offset:38912
	s_waitcnt vmcnt(0) lgkmcnt(0)
	s_barrier
	v_mfma_f32_32x32x16_bf16 v[112:127], v[128:131], v[132:135], v[112:127]
	v_mfma_f32_32x32x16_bf16 v[80:95], v[128:131], v[140:143], v[80:95]
	v_mfma_f32_32x32x16_bf16 v[48:63], v[128:131], v[144:147], v[48:63]
	v_mfma_f32_32x32x16_bf16 v[16:31], v[128:131], v[148:151], v[16:31]
	v_mfma_f32_32x32x16_bf16 v[96:111], v[136:139], v[132:135], v[96:111]
	v_mfma_f32_32x32x16_bf16 v[64:79], v[136:139], v[140:143], v[64:79]
	v_mfma_f32_32x32x16_bf16 v[32:47], v[136:139], v[144:147], v[32:47]
	v_mov_b32_e32 v145, v200
	v_mfma_f32_32x32x16_bf16 v[0:15], v[136:139], v[148:151], v[0:15]
	s_cbranch_scc0 .LBB0_223
	s_cmpk_gt_u32 s58, 0x1ff
	s_cbranch_scc0 .LBB0_220
	s_cmpk_lt_u32 s58, 0x400
	s_mov_b64 s[6:7], 0
	s_cbranch_scc1 .LBB0_214
	s_cmpk_gt_u32 s58, 0x57f
	s_mov_b64 s[42:43], -1
	s_cbranch_scc0 .LBB0_218
	s_cmpk_gt_u32 s58, 0x5ff
	s_mov_b64 s[34:35], -1
	s_cbranch_scc0 .LBB0_216
	s_cmpk_lt_u32 s58, 0x800
	s_mov_b64 s[34:35], 0
	s_cbranch_scc1 .LBB0_215
	s_cmpk_gt_u32 s58, 0x97f
	s_cbranch_scc0 .LBB0_212
	s_cmpk_gt_u32 s58, 0xaff
	s_mov_b64 s[42:43], 0
	s_cbranch_scc1 .LBB0_291
	s_load_dwordx2 s[4:5], s[0:1], 0x98
	v_readlane_b32 s8, v255, 36
	v_readlane_b32 s9, v255, 37
	s_lshl_b64 s[8:9], s[8:9], 2
	s_mov_b64 s[28:29], -1
	s_waitcnt lgkmcnt(0)
	s_add_u32 s4, s4, s8
	s_addc_u32 s5, s5, s9
	s_mov_b64 s[8:9], 0

; DI int otid() { int t = threadIdx.x; asm volatile("" : "+v"(t)); return t; }
; template <bool VMODE, int TJ>
; DI void gemm_mainloop(const bf16_t* __restrict__ W, const bf16_t* __restrict__ X, int NW, char* smem, f32x16 (&acc)[2][TJ]) {
;     constexpr int XROWS = 64 * TJ, STAGE = (128 + XROWS) * 64, NPW = 2 + TJ;
;     const int tid = otid(), lane = tid & 63, wave = tid >> 6, r = lane & 31, h = lane >> 5, wf = wave & 1, wt = wave >> 1;
;     const int goff = (16 * wave + (lane >> 2)) * 32 + (((lane & 3) ^ (lane >> 4)) << 3);
;     const bf16_t* wp = W + goff;
;     const bf16_t* xp = X + goff;
;     const size_t wks = (size_t)NW * 32, xks = (size_t)NTOK * 32;
;     char* ld = smem + tid * 16;
;     ...
;     const int xr = (r >> 2) & 3;
;     const int fo0 = r * 64 + (((0 + h) ^ xr) << 4), fo1 = r * 64 + (((2 + h) ^ xr) << 4);
;     __syncthreads();
; DI void inproj_phase(const Params& p, int l, char* smem) {
;     ...
;         const int n0 = nt * 128;
;         const bf16_t* W = p.wtin + (size_t)l * INW * D + (size_t)n0 * 32;
;         const bf16_t* X = p.hmix + (size_t)mtile * 256 * 32;
;         f32x16 acc[2][4];
;         zero_acc<4>(acc);
;         int vf0 = -1;
;         if (n0 >= 512 && n0 < 768) vf0 = n0 - 512;
;         else if (n0 >= 1536 && n0 < 1664) vf0 = 256 + (n0 - 1536);
;         else if (n0 >= 2816 && n0 < 3200) vf0 = 384 + (n0 - 2816);
;         if (vf0 >= 0) { gemm_mainloop<true, 4>(W, X, INW, smem, acc); epi_v(p, mtile, vf0, acc, smem); }
.LBB0_287:
	s_and_b64 vcc, exec, s[4:5]
	s_cbranch_vccz .LBB0_185
	v_mov_b32_e32 v4, v200
	s_movk_i32 s4, 0xffe0
	v_bfe_u32 v1, v4, 4, 2
	v_bitop3_b32 v1, v1, v4, 3 bitop3:0x78
	v_lshlrev_b32_e32 v0, 3, v4
	v_lshlrev_b32_e32 v1, 3, v1
	v_and_or_b32 v0, v0, s4, v1
	v_bfe_u32 v5, v4, 5, 1
	v_ashrrev_i32_e32 v1, 31, v0
	v_lshl_add_u32 v130, v4, 4, 32
	v_bfe_u32 v7, v4, 2, 2
	v_lshlrev_b64 v[128:129], 1, v[0:1]
	v_bitop3_b32 v9, v5, v7, 2 bitop3:0x36
	v_readfirstlane_b32 s5, v130
	v_add_u32_e32 v7, 0x1000, v130
	v_lshl_add_u64 v[0:1], s[52:53], 0, v[128:129]
	v_lshrrev_b32_e32 v6, 2, v4
	s_mov_b32 m0, s5
	v_readfirstlane_b32 s5, v7
	v_lshlrev_b32_e32 v8, 6, v4
	v_bitop3_b32 v6, v5, v6, 3 bitop3:0x78
	s_barrier
	global_load_lds_dwordx4 v[0:1], off
	v_lshl_add_u64 v[4:5], v[0:1], 0, s[26:27]
	s_mov_b32 m0, s5
	v_add_u32_e32 v7, 0x3000, v130
	global_load_lds_dwordx4 v[4:5], off
	v_add_u32_e32 v4, 0x2000, v130
	v_lshl_add_u64 v[2:3], s[56:57], 0, v[128:129]
	v_readfirstlane_b32 s5, v4
	s_mov_b32 m0, s5
	v_readfirstlane_b32 s5, v7
	v_add_u32_e32 v7, 0x4000, v130
	global_load_lds_dwordx4 v[2:3], off
	v_lshl_add_u64 v[4:5], v[2:3], 0, s[26:27]
	s_mov_b32 m0, s5
	v_readfirstlane_b32 s5, v7
	v_add_u32_e32 v7, 0x5000, v130
	global_load_lds_dwordx4 v[4:5], off
	v_lshl_add_u64 v[4:5], v[2:3], 0, s[16:17]
	s_mov_b32 m0, s5
	v_readfirstlane_b32 s5, v7
	v_add_u32_e32 v11, 0x6000, v130
	global_load_lds_dwordx4 v[4:5], off
	v_lshl_add_u64 v[4:5], v[2:3], 0, s[90:91]
	s_mov_b32 m0, s5
	s_mov_b64 s[6:7], 0x38000
	v_readfirstlane_b32 s5, v11
	global_load_lds_dwordx4 v[4:5], off
	v_lshl_add_u64 v[4:5], v[0:1], 0, s[6:7]
	s_mov_b32 m0, s5
	v_and_b32_e32 v10, 0x7c0, v8
	s_mov_b64 s[6:7], 0x120000
	global_load_lds_dwordx4 v[4:5], off
	v_add_u32_e32 v4, 0x7000, v130
	v_lshl_or_b32 v131, v6, 4, v10
	v_lshl_add_u64 v[6:7], v[2:3], 0, s[6:7]
	s_mov_b64 s[6:7], 0x39000
	v_readfirstlane_b32 s5, v4
	v_lshl_add_u64 v[0:1], v[0:1], 0, s[6:7]
	s_mov_b32 m0, s5
	v_add_u32_e32 v4, 0x9000, v130
	global_load_lds_dwordx4 v[0:1], off
	v_add_u32_e32 v0, 0x8000, v130
	s_mov_b64 s[6:7], 0x121000
	v_readfirstlane_b32 s5, v0
	s_mov_b32 m0, s5
	v_readfirstlane_b32 s5, v4
	v_add_u32_e32 v4, 0xa000, v130
	global_load_lds_dwordx4 v[6:7], off
	v_lshl_add_u64 v[0:1], v[2:3], 0, s[6:7]
	s_mov_b32 m0, s5
	s_mov_b64 s[6:7], 0x122000
	v_readfirstlane_b32 s5, v4
	global_load_lds_dwordx4 v[0:1], off
	v_lshl_add_u64 v[0:1], v[2:3], 0, s[6:7]
	s_mov_b32 m0, s5
	s_mov_b64 s[6:7], 0x123000
	global_load_lds_dwordx4 v[0:1], off
	v_lshl_add_u64 v[0:1], v[2:3], 0, s[6:7]
	v_add_u32_e32 v2, 0xb000, v130
	s_mov_b32 s4, 2
	v_readfirstlane_b32 s5, v2
	s_mov_b32 m0, s5
	v_lshl_or_b32 v132, v9, 4, v10
	global_load_lds_dwordx4 v[0:1], off
	v_mov_b32_e32 v0, 0
	v_and_b32_e32 v134, 0x1000, v8
	v_and_b32_e32 v133, 0xffffe000, v8
	s_mov_b32 s6, 0
	s_mov_b32 s5, 30
	v_mov_b32_e32 v1, v0
	v_mov_b32_e32 v2, v0
	v_mov_b32_e32 v3, v0
	v_mov_b32_e32 v4, v0
	v_mov_b32_e32 v5, v0
	v_mov_b32_e32 v6, v0
	v_mov_b32_e32 v7, v0
	v_mov_b32_e32 v8, v0
	v_mov_b32_e32 v9, v0
	v_mov_b32_e32 v10, v0
	v_mov_b32_e32 v11, v0
	v_mov_b32_e32 v12, v0
	v_mov_b32_e32 v13, v0
	v_mov_b32_e32 v14, v0
	v_mov_b32_e32 v15, v0
	v_mov_b32_e32 v16, v0
	v_mov_b32_e32 v17, v0
	v_mov_b32_e32 v18, v0
	v_mov_b32_e32 v19, v0
	v_mov_b32_e32 v20, v0
	v_mov_b32_e32 v21, v0
	v_mov_b32_e32 v22, v0
	v_mov_b32_e32 v23, v0
	v_mov_b32_e32 v24, v0
	v_mov_b32_e32 v25, v0
	v_mov_b32_e32 v26, v0
	v_mov_b32_e32 v27, v0
	v_mov_b32_e32 v28, v0
	v_mov_b32_e32 v29, v0
	v_mov_b32_e32 v30, v0
	v_mov_b32_e32 v31, v0
	v_mov_b32_e32 v32, v0
	v_mov_b32_e32 v33, v0
	v_mov_b32_e32 v34, v0
	v_mov_b32_e32 v35, v0
	v_mov_b32_e32 v36, v0
	v_mov_b32_e32 v37, v0
	v_mov_b32_e32 v38, v0
	v_mov_b32_e32 v39, v0
	v_mov_b32_e32 v40, v0
	v_mov_b32_e32 v41, v0
	v_mov_b32_e32 v42, v0
	v_mov_b32_e32 v43, v0
	v_mov_b32_e32 v44, v0
	v_mov_b32_e32 v45, v0
	v_mov_b32_e32 v46, v0
	v_mov_b32_e32 v47, v0
	v_mov_b32_e32 v48, v0
	v_mov_b32_e32 v49, v0
	v_mov_b32_e32 v50, v0
	v_mov_b32_e32 v51, v0
	v_mov_b32_e32 v52, v0
	v_mov_b32_e32 v53, v0
	v_mov_b32_e32 v54, v0
	v_mov_b32_e32 v55, v0
	v_mov_b32_e32 v56, v0
	v_mov_b32_e32 v57, v0
	v_mov_b32_e32 v58, v0
	v_mov_b32_e32 v59, v0
	v_mov_b32_e32 v60, v0
	v_mov_b32_e32 v61, v0
	v_mov_b32_e32 v62, v0
	v_mov_b32_e32 v63, v0
	v_mov_b32_e32 v64, v0
	v_mov_b32_e32 v65, v0
	v_mov_b32_e32 v66, v0
	v_mov_b32_e32 v67, v0
	v_mov_b32_e32 v68, v0
	v_mov_b32_e32 v69, v0
	v_mov_b32_e32 v70, v0
	v_mov_b32_e32 v71, v0
	v_mov_b32_e32 v72, v0
	v_mov_b32_e32 v73, v0
	v_mov_b32_e32 v74, v0
	v_mov_b32_e32 v75, v0
	v_mov_b32_e32 v76, v0
	v_mov_b32_e32 v77, v0
	v_mov_b32_e32 v78, v0
	v_mov_b32_e32 v79, v0
	v_mov_b32_e32 v80, v0
	v_mov_b32_e32 v81, v0
	v_mov_b32_e32 v82, v0
	v_mov_b32_e32 v83, v0
	v_mov_b32_e32 v84, v0
	v_mov_b32_e32 v85, v0
	v_mov_b32_e32 v86, v0
	v_mov_b32_e32 v87, v0
	v_mov_b32_e32 v88, v0
	v_mov_b32_e32 v89, v0
	v_mov_b32_e32 v90, v0
	v_mov_b32_e32 v91, v0
	v_mov_b32_e32 v92, v0
	v_mov_b32_e32 v93, v0
	v_mov_b32_e32 v94, v0
	v_mov_b32_e32 v95, v0
	v_mov_b32_e32 v96, v0
	v_mov_b32_e32 v97, v0
	v_mov_b32_e32 v98, v0
	v_mov_b32_e32 v99, v0
	v_mov_b32_e32 v100, v0
	v_mov_b32_e32 v101, v0
	v_mov_b32_e32 v102, v0
	v_mov_b32_e32 v103, v0
	v_mov_b32_e32 v104, v0
	v_mov_b32_e32 v105, v0
	v_mov_b32_e32 v106, v0
	v_mov_b32_e32 v107, v0
	v_mov_b32_e32 v108, v0
	v_mov_b32_e32 v109, v0
	v_mov_b32_e32 v110, v0
	v_mov_b32_e32 v111, v0
	v_mov_b32_e32 v112, v0
	v_mov_b32_e32 v113, v0
	v_mov_b32_e32 v114, v0
	v_mov_b32_e32 v115, v0
	v_mov_b32_e32 v116, v0
	v_mov_b32_e32 v117, v0
	v_mov_b32_e32 v118, v0
	v_mov_b32_e32 v119, v0
	v_mov_b32_e32 v120, v0
	v_mov_b32_e32 v121, v0
	v_mov_b32_e32 v122, v0
	v_mov_b32_e32 v123, v0
	v_mov_b32_e32 v124, v0
	v_mov_b32_e32 v125, v0
	v_mov_b32_e32 v126, v0
	v_mov_b32_e32 v127, v0
	v_readfirstlane_b32 s100, v130
	v_add_u32_e32 v170, 0x38000, v128
	v_add_u32_e32 v171, 0x39000, v128
	v_add_u32_e32 v172, 0x120000, v128
	v_add_u32_e32 v173, 0x121000, v128
	v_add_u32_e32 v174, 0x122000, v128
	v_add_u32_e32 v175, 0x123000, v128
; #define MFMA(a, b, c) __builtin_amdgcn_mfma_f32_32x32x16_bf16((a), (b), (c), 0, 0, 0)
; #define G_ISSUE(ks_, buf_) do { \
;     const bf16_t* wq_ = wp + (ks_) * wks; const bf16_t* xq_ = xp + (ks_) * xks; char* lb_ = ld + (buf_) * STAGE; \
;     dma16(wq_, lb_); dma16(wq_ + 2048, lb_ + 4096); \
;     _Pragma("unroll") for (int i_ = 0; i_ < TJ; ++i_) dma16(xq_ + i_ * 2048, lb_ + 8192 + i_ * 4096); } while (0)
; template <bool VMODE, int TJ>
; DI void gemm_mainloop(const bf16_t* __restrict__ W, const bf16_t* __restrict__ X, int NW, char* smem, f32x16 (&acc)[2][TJ]) {
;     ...
;         for (int ks = 0; ks < 32; ++ks) {
;             if (ks < 31) asm volatile("s_waitcnt vmcnt(6)" ::: "memory");
;             else asm volatile("s_waitcnt vmcnt(0)" ::: "memory");
;             __builtin_amdgcn_s_barrier();
;             const char* sw = smem + bc * STAGE + wf * 64 * 64;
;             const char* sx = smem + bc * STAGE + 8192 + wt * (32 * TJ) * 64;
;             bf16x8 fw[2], fx[TJ], gw[2], gx[TJ];
; #pragma unroll
;             for (int i = 0; i < 2; ++i) fw[i] = *(const bf16x8*)(sw + i * 32 * 64 + fo0);
; #pragma unroll
;             for (int j = 0; j < TJ; ++j) fx[j] = *(const bf16x8*)(sx + j * 32 * 64 + fo0);
;             __builtin_amdgcn_sched_barrier(0);
;             if (ks + 2 < 32) G_ISSUE(ks + 2, bn);
;             __builtin_amdgcn_sched_barrier(0);
; #pragma unroll
;             for (int i = 0; i < 2; ++i) gw[i] = *(const bf16x8*)(sw + i * 32 * 64 + fo1);
; #pragma unroll
;             for (int j = 0; j < TJ; ++j) gx[j] = *(const bf16x8*)(sx + j * 32 * 64 + fo1);
; #pragma unroll
;             for (int i = 0; i < 2; ++i)
; #pragma unroll
;                 for (int j = 0; j < TJ; ++j) acc[i][j] = VMODE ? MFMA(fx[j], fw[i], acc[i][j]) : MFMA(fw[i], fx[j], acc[i][j]);
; #pragma unroll
;             for (int i = 0; i < 2; ++i)
; #pragma unroll
;                 for (int j = 0; j < TJ; ++j) acc[i][j] = VMODE ? MFMA(gx[j], gw[i], acc[i][j]) : MFMA(gw[i], gx[j], acc[i][j]);
;             bc = (bc == 2) ? 0 : bc + 1; bn = (bn == 2) ? 0 : bn + 1;
;         }
.LBB0_289:
	s_mul_i32 s7, s6, 0x6000
	s_add_i32 s7, s7, 32
	v_add_u32_e32 v135, s7, v134
	v_add_u32_e32 v168, s7, v133
	v_add_u32_e32 v140, v135, v131
	v_add_u32_e32 v156, v168, v131
	s_waitcnt vmcnt(6)
	s_barrier
	ds_read_b128 v[136:139], v140
	ds_read_b128 v[140:143], v140 offset:2048
	ds_read_b128 v[144:147], v156 offset:8192
	ds_read_b128 v[148:151], v156 offset:10240
	ds_read_b128 v[152:155], v156 offset:12288
	ds_read_b128 v[156:159], v156 offset:14336
	s_mul_i32 s7, s4, 0x6000
	s_add_i32 s101, s7, s100
	s_add_i32 s7, s6, 1
	s_cmp_lg_u32 s6, 2
	s_cselect_b32 s6, s7, 0
	s_add_i32 s7, s4, 1
	s_cmp_lg_u32 s4, 2
	s_cselect_b32 s4, s7, 0
	s_add_i32 s5, s5, -1
	s_add_u32 s56, s56, 0x120000
	s_addc_u32 s57, s57, 0
	s_add_u32 s52, s52, 0x38000
	s_addc_u32 s53, s53, 0
	s_mov_b32 m0, s101
	s_waitcnt lgkmcnt(0)
	v_mfma_f32_32x32x16_bf16 v[112:127], v[144:147], v[136:139], v[112:127]
	global_load_lds_dwordx4 v170, s[52:53]
	s_add_u32 m0, s101, 0x1000
	v_add_u32_e32 v160, v168, v132
	v_add_u32_e32 v135, v135, v132
	v_mfma_f32_32x32x16_bf16 v[96:111], v[148:151], v[136:139], v[96:111]
	global_load_lds_dwordx4 v171, s[52:53]
	s_add_u32 m0, s101, 0x2000
	v_mfma_f32_32x32x16_bf16 v[80:95], v[152:155], v[136:139], v[80:95]
	global_load_lds_dwordx4 v172, s[56:57]
	s_add_u32 m0, s101, 0x3000
	v_mfma_f32_32x32x16_bf16 v[64:79], v[156:159], v[136:139], v[64:79]
	global_load_lds_dwordx4 v173, s[56:57]
	s_add_u32 m0, s101, 0x4000
	v_mfma_f32_32x32x16_bf16 v[48:63], v[144:147], v[140:143], v[48:63]
	global_load_lds_dwordx4 v174, s[56:57]
	s_add_u32 m0, s101, 0x5000
	v_mfma_f32_32x32x16_bf16 v[32:47], v[148:151], v[140:143], v[32:47]
	global_load_lds_dwordx4 v175, s[56:57]
	v_mfma_f32_32x32x16_bf16 v[16:31], v[152:155], v[140:143], v[16:31]
	v_mfma_f32_32x32x16_bf16 v[0:15], v[156:159], v[140:143], v[0:15]
	ds_read_b128 v[136:139], v160 offset:8192
	ds_read_b128 v[140:143], v135
	ds_read_b128 v[144:147], v135 offset:2048
	ds_read_b128 v[148:151], v160 offset:10240
	ds_read_b128 v[152:155], v160 offset:12288
	ds_read_b128 v[156:159], v160 offset:14336
	s_waitcnt lgkmcnt(0)
	v_mfma_f32_32x32x16_bf16 v[112:127], v[136:139], v[140:143], v[112:127]
	v_mfma_f32_32x32x16_bf16 v[96:111], v[148:151], v[140:143], v[96:111]
	v_mfma_f32_32x32x16_bf16 v[80:95], v[152:155], v[140:143], v[80:95]
	v_mfma_f32_32x32x16_bf16 v[64:79], v[156:159], v[140:143], v[64:79]
	v_mfma_f32_32x32x16_bf16 v[48:63], v[136:139], v[144:147], v[48:63]
	v_mfma_f32_32x32x16_bf16 v[32:47], v[148:151], v[144:147], v[32:47]
	v_mfma_f32_32x32x16_bf16 v[16:31], v[152:155], v[144:147], v[16:31]
	v_mfma_f32_32x32x16_bf16 v[0:15], v[156:159], v[144:147], v[0:15]
	s_cmp_lg_u32 s5, 0
	s_cbranch_scc1 .LBB0_289
	v_add_u32_e32 v154, 32, v134
	v_add_u32_e32 v133, 32, v133
	v_add_u32_e32 v155, v154, v131
	v_add_u32_e32 v156, v133, v131
	s_waitcnt vmcnt(6)
	s_barrier
	ds_read_b128 v[134:137], v155
	ds_read_b128 v[138:141], v155 offset:2048
	ds_read_b128 v[128:131], v156 offset:8192
	ds_read_b128 v[142:145], v156 offset:10240
	ds_read_b128 v[146:149], v156 offset:12288
	ds_read_b128 v[150:153], v156 offset:14336
	v_add_u32_e32 v172, v133, v132
	s_waitcnt lgkmcnt(0)
	v_mfma_f32_32x32x16_bf16 v[112:127], v[128:131], v[134:137], v[112:127]
	v_add_u32_e32 v160, v154, v132
	v_mfma_f32_32x32x16_bf16 v[48:63], v[128:131], v[138:141], v[48:63]
	ds_read_b128 v[128:131], v172 offset:8192
	v_mfma_f32_32x32x16_bf16 v[96:111], v[142:145], v[134:137], v[96:111]
	v_mfma_f32_32x32x16_bf16 v[80:95], v[146:149], v[134:137], v[80:95]
	v_mfma_f32_32x32x16_bf16 v[64:79], v[150:153], v[134:137], v[64:79]
	v_mfma_f32_32x32x16_bf16 v[32:47], v[142:145], v[138:141], v[32:47]
	v_mfma_f32_32x32x16_bf16 v[16:31], v[146:149], v[138:141], v[16:31]
	v_mfma_f32_32x32x16_bf16 v[0:15], v[150:153], v[138:141], v[0:15]
	ds_read_b128 v[132:135], v160
	ds_read_b128 v[136:139], v160 offset:2048
	ds_read_b128 v[140:143], v172 offset:10240
	ds_read_b128 v[144:147], v172 offset:12288
	ds_read_b128 v[148:151], v172 offset:14336
	s_waitcnt vmcnt(0)
	s_barrier
	s_waitcnt lgkmcnt(0)
	v_mfma_f32_32x32x16_bf16 v[112:127], v[128:131], v[132:135], v[112:127]
	v_mfma_f32_32x32x16_bf16 v[96:111], v[140:143], v[132:135], v[96:111]
	v_mfma_f32_32x32x16_bf16 v[80:95], v[144:147], v[132:135], v[80:95]
	v_mfma_f32_32x32x16_bf16 v[64:79], v[148:151], v[132:135], v[64:79]
	v_mfma_f32_32x32x16_bf16 v[48:63], v[128:131], v[136:139], v[48:63]
	v_mfma_f32_32x32x16_bf16 v[32:47], v[140:143], v[136:139], v[32:47]
	v_mfma_f32_32x32x16_bf16 v[16:31], v[144:147], v[136:139], v[16:31]
	ds_read_b128 v[128:131], v155 offset:24576
	ds_read_b128 v[132:135], v155 offset:26624
	ds_read_b128 v[140:143], v156 offset:32768
	ds_read_b128 v[144:147], v156 offset:34816
	ds_read_b128 v[152:155], v156 offset:36864
	ds_read_b128 v[156:159], v156 offset:38912
	v_mfma_f32_32x32x16_bf16 v[0:15], v[148:151], v[136:139], v[0:15]
	s_waitcnt lgkmcnt(0)
	v_mfma_f32_32x32x16_bf16 v[112:127], v[140:143], v[128:131], v[112:127]
	ds_read_b128 v[136:139], v160 offset:24576
	ds_read_b128 v[148:151], v160 offset:26624
	ds_read_b128 v[160:163], v172 offset:32768
	ds_read_b128 v[164:167], v172 offset:34816
	ds_read_b128 v[168:171], v172 offset:36864
	ds_read_b128 v[172:175], v172 offset:38912
	s_waitcnt vmcnt(0) lgkmcnt(0)
	s_barrier
; DI unsigned pk2(float a, float b) { f2_t v = {a, b}; bf2_t r = __builtin_convertvector(v, bf2_t); return __builtin_bit_cast(unsigned, r); }
; DI int otid() { int t = threadIdx.x; asm volatile("" : "+v"(t)); return t; }
; template <int NIT>
; DI void stage_flush_bf16(const char* sb, bf16_t* gdst, int lane) {
; #pragma unroll
;     for (int it = 0; it < NIT; ++it) {
;         const int c = lane + 64 * it, row = c >> 3, lc = (c & 7) ^ (row & 7);
;         const u32x4_t v = *(const u32x4_t*)(sb + c * 16);
;         *(u32x4_t*)(gdst + row * 64 + lc * 8) = v;
;     }
; DI void epi_v(const Params& p, int mtile, int vf0, f32x16 (&acc)[2][4], char* smem) {
;     const int tid = otid(), lane = tid & 63, wave = tid >> 6, r = lane & 31, h = lane >> 5, wf = wave & 1, wt = wave >> 1;
;     const int b = mtile / 9, t0 = (mtile % 9) * 256;
;     char* sb = smem + wave * 16384;
; #pragma unroll
;     for (int i = 0; i < 2; ++i)
; #pragma unroll
;         for (int j = 0; j < 4; ++j)
; #pragma unroll
;             for (int q = 0; q < 4; ++q) {
;                 uint2 o; o.x = pk2(acc[i][j][4 * q], acc[i][j][4 * q + 1]); o.y = pk2(acc[i][j][4 * q + 2], acc[i][j][4 * q + 3]);
;                 stage_quad_bf16(sb + (j >> 1) * 8192, 32 * i + r, 4 * (j & 1) + 2 * (q >> 1) + h, q & 1, o);
;             }
;     bf16_t* g0 = p.vT + (((size_t)b * 12 + (vf0 >> 6) + wf) * 36 + (t0 >> 6) + 2 * wt) * 4096;
;     stage_flush_bf16<8>(sb, g0, lane);
;     stage_flush_bf16<8>(sb + 8192, g0 + 4096, lane);
	s_lshr_b32 s4, s47, 31
	s_ashr_i32 s5, s47, 1
	s_add_i32 s6, s5, s4
	v_mfma_f32_32x32x16_bf16 v[96:111], v[144:147], v[128:131], v[96:111]
	s_mul_i32 s4, s6, 9
	s_sub_i32 s8, s50, s4
	s_mul_hi_i32 s7, s6, 12
	s_mul_i32 s6, s6, 12
	s_lshr_b32 s9, s46, 6
	s_add_u32 s6, s6, s9
	s_addc_u32 s7, s7, 0
	v_mfma_f32_32x32x16_bf16 v[0:15], v[156:159], v[132:135], v[0:15]
	v_mfma_f32_32x32x16_bf16 v[112:127], v[160:163], v[136:139], v[112:127]
	v_mfma_f32_32x32x16_bf16 v[96:111], v[164:167], v[136:139], v[96:111]
	s_nop 10
	v_cvt_pk_bf16_f32 v112, v112, v113
	v_cvt_pk_bf16_f32 v113, v114, v115
	v_cvt_pk_bf16_f32 v115, v118, v119
	v_mfma_f32_32x32x16_bf16 v[32:47], v[144:147], v[132:135], v[32:47]
	v_cvt_pk_bf16_f32 v96, v96, v97
	v_cvt_pk_bf16_f32 v97, v98, v99
	v_cvt_pk_bf16_f32 v99, v102, v103
	v_mfma_f32_32x32x16_bf16 v[80:95], v[152:155], v[128:131], v[80:95]
	v_mfma_f32_32x32x16_bf16 v[64:79], v[156:159], v[128:131], v[64:79]
	v_mov_b32_e32 v128, v200
	s_load_dwordx2 s[4:5], s[0:1], 0xc8
	v_ashrrev_i32_e32 v130, 6, v128
	v_bfe_u32 v131, v128, 5, 1
	v_bitop3_b32 v114, v131, v128, 7 bitop3:0x78
	v_and_b32_e32 v192, 1, v130
	v_mfma_f32_32x32x16_bf16 v[0:15], v[172:175], v[148:151], v[0:15]
	v_and_b32_e32 v129, 63, v128
	v_mfma_f32_32x32x16_bf16 v[48:63], v[140:143], v[132:135], v[48:63]
	s_nop 9
	v_cvt_pk_bf16_f32 v0, v0, v1
	v_cvt_pk_bf16_f32 v1, v2, v3
	v_cvt_pk_bf16_f32 v2, v4, v5
	v_cvt_pk_bf16_f32 v3, v6, v7
	v_bfe_u32 v6, v128, 3, 3
	v_mfma_f32_32x32x16_bf16 v[16:31], v[152:155], v[132:135], v[16:31]
	v_lshlrev_b32_e32 v133, 7, v128
	v_lshl_add_u32 v132, v130, 14, 32
	v_and_b32_e32 v133, 0xf80, v133
	v_add_u32_e32 v133, v132, v133
	v_and_b32_e32 v134, 7, v128
	v_lshl_add_u32 v135, v114, 4, v133
	v_cvt_pk_bf16_f32 v114, v116, v117
	ds_write_b128 v135, v[112:115]
	v_bitop3_b32 v114, v131, v134, 2 bitop3:0x36
	v_cvt_pk_bf16_f32 v112, v120, v121
	v_cvt_pk_bf16_f32 v113, v122, v123
	v_lshl_add_u32 v116, v114, 4, v133
	v_cvt_pk_bf16_f32 v114, v124, v125
	v_cvt_pk_bf16_f32 v115, v126, v127
	v_bitop3_b32 v98, v131, v134, 4 bitop3:0x36
	v_mfma_f32_32x32x16_bf16 v[32:47], v[164:167], v[148:151], v[32:47]
	ds_write_b128 v116, v[112:115]
	v_lshl_add_u32 v112, v98, 4, v133
	v_cvt_pk_bf16_f32 v98, v100, v101
	ds_write_b128 v112, v[96:99]
	v_bitop3_b32 v98, v131, v134, 6 bitop3:0x36
	v_lshl_add_u32 v100, v98, 4, v133
	ds_write_b128 v112, v[0:3] offset:12288
	v_cvt_pk_bf16_f32 v0, v8, v9
	v_cvt_pk_bf16_f32 v1, v10, v11
	v_cvt_pk_bf16_f32 v2, v12, v13
	v_cvt_pk_bf16_f32 v3, v14, v15
	v_mfma_f32_32x32x16_bf16 v[16:31], v[168:171], v[148:151], v[16:31]
	ds_write_b128 v100, v[0:3] offset:12288
	v_and_b32_e32 v2, -2, v130
	v_lshl_add_u32 v2, s8, 2, v2
	v_lshl_add_u64 v[0:1], s[6:7], 0, v[192:193]
	v_ashrrev_i32_e32 v3, 31, v2
	v_mad_u64_u32 v[2:3], s[6:7], v0, 36, v[2:3]
	v_cvt_pk_bf16_f32 v96, v104, v105
	v_cvt_pk_bf16_f32 v97, v106, v107
	v_cvt_pk_bf16_f32 v98, v108, v109
	v_cvt_pk_bf16_f32 v99, v110, v111
	v_mad_i32_i24 v3, v1, 36, v3
	ds_write_b128 v100, v[96:99]
	v_cvt_pk_bf16_f32 v32, v32, v33
	v_cvt_pk_bf16_f32 v33, v34, v35
	v_cvt_pk_bf16_f32 v34, v36, v37
	v_lshlrev_b64 v[0:1], 13, v[2:3]
	v_lshl_add_u32 v37, v129, 4, v132
	s_waitcnt lgkmcnt(0)
	v_lshl_add_u64 v[4:5], s[4:5], 0, v[0:1]
	ds_read_b128 v[0:3], v37
	v_xor_b32_e32 v8, v6, v128
	v_cvt_pk_bf16_f32 v16, v16, v17
	v_cvt_pk_bf16_f32 v17, v18, v19
	v_cvt_pk_bf16_f32 v18, v20, v21
	v_cvt_pk_bf16_f32 v19, v22, v23
	v_lshlrev_b32_e32 v192, 7, v6
	v_lshlrev_b32_e32 v8, 4, v8
	ds_write_b128 v135, v[16:19] offset:12288
	v_cvt_pk_bf16_f32 v19, v30, v31
	v_lshl_add_u64 v[6:7], v[4:5], 0, v[192:193]
	v_and_b32_e32 v30, 0x70, v8
	v_mov_b32_e32 v31, v193
	v_lshl_add_u64 v[6:7], v[6:7], 0, v[30:31]
	v_cvt_pk_bf16_f32 v35, v38, v39
	s_waitcnt lgkmcnt(1)
	global_store_dwordx4 v[6:7], v[0:3], off
	ds_write_b128 v112, v[32:35] offset:4096
	v_cvt_pk_bf16_f32 v34, v44, v45
	v_or_b32_e32 v0, 64, v129
	v_lshl_add_u32 v44, v0, 4, v132
	v_lshrrev_b32_e32 v6, 3, v0
	ds_read_b128 v[0:3], v44
	v_xor_b32_e32 v8, v6, v128
	v_cvt_pk_bf16_f32 v17, v26, v27
	v_lshlrev_b32_e32 v26, 7, v6
	v_mov_b32_e32 v27, v193
	v_lshlrev_b32_e32 v8, 4, v8
	v_cvt_pk_bf16_f32 v18, v28, v29
	v_lshl_add_u64 v[6:7], v[4:5], 0, v[26:27]
	v_and_b32_e32 v28, 0x70, v8
	v_mov_b32_e32 v29, v193
	v_lshl_add_u64 v[6:7], v[6:7], 0, v[28:29]
	s_waitcnt lgkmcnt(0)
	global_store_dwordx4 v[6:7], v[0:3], off
	v_mov_b32_e32 v23, v193
	v_mfma_f32_32x32x16_bf16 v[48:63], v[160:163], v[148:151], v[48:63]
	v_or_b32_e32 v0, 0x80, v129
	v_lshl_add_u32 v45, v0, 4, v132
	v_lshrrev_b32_e32 v6, 3, v0
	ds_read_b128 v[0:3], v45
	v_xor_b32_e32 v8, v6, v128
	v_lshlrev_b32_e32 v22, 7, v6
	v_lshlrev_b32_e32 v8, 4, v8
	v_cvt_pk_bf16_f32 v16, v24, v25
	v_lshl_add_u64 v[6:7], v[4:5], 0, v[22:23]
	v_and_b32_e32 v24, 0x70, v8
	v_mov_b32_e32 v25, v193
	v_lshl_add_u64 v[6:7], v[6:7], 0, v[24:25]
	s_waitcnt lgkmcnt(0)
; DI unsigned pk2(float a, float b) { f2_t v = {a, b}; bf2_t r = __builtin_convertvector(v, bf2_t); return __builtin_bit_cast(unsigned, r); }
; template <int NIT>
; DI void stage_flush_bf16(const char* sb, bf16_t* gdst, int lane) {
; #pragma unroll
;     for (int it = 0; it < NIT; ++it) {
;         const int c = lane + 64 * it, row = c >> 3, lc = (c & 7) ^ (row & 7);
;         const u32x4_t v = *(const u32x4_t*)(sb + c * 16);
;         *(u32x4_t*)(gdst + row * 64 + lc * 8) = v;
;     }
; DI void epi_v(const Params& p, int mtile, int vf0, f32x16 (&acc)[2][4], char* smem) {
;     ...
;                 uint2 o; o.x = pk2(acc[i][j][4 * q], acc[i][j][4 * q + 1]); o.y = pk2(acc[i][j][4 * q + 2], acc[i][j][4 * q + 3]);
;                 stage_quad_bf16(sb + (j >> 1) * 8192, 32 * i + r, 4 * (j & 1) + 2 * (q >> 1) + h, q & 1, o);
;             }
;     bf16_t* g0 = p.vT + (((size_t)b * 12 + (vf0 >> 6) + wf) * 36 + (t0 >> 6) + 2 * wt) * 4096;
;     stage_flush_bf16<8>(sb, g0, lane);
;     stage_flush_bf16<8>(sb + 8192, g0 + 4096, lane);
	global_store_dwordx4 v[6:7], v[0:3], off
	ds_write_b128 v116, v[16:19] offset:12288
	v_mov_b32_e32 v19, v193
	v_or_b32_e32 v0, 0xc0, v129
	v_lshl_add_u32 v36, v0, 4, v132
	v_lshrrev_b32_e32 v6, 3, v0
	ds_read_b128 v[0:3], v36
	v_xor_b32_e32 v8, v6, v128
	v_lshlrev_b32_e32 v18, 7, v6
	v_lshlrev_b32_e32 v8, 4, v8
	v_lshl_add_u64 v[6:7], v[4:5], 0, v[18:19]
	v_and_b32_e32 v20, 0x70, v8
	v_mov_b32_e32 v21, v193
	v_cvt_pk_bf16_f32 v48, v48, v49
	v_cvt_pk_bf16_f32 v49, v50, v51
	v_cvt_pk_bf16_f32 v50, v52, v53
	v_cvt_pk_bf16_f32 v51, v54, v55
	v_lshl_add_u64 v[6:7], v[6:7], 0, v[20:21]
	ds_write_b128 v135, v[48:51] offset:4096
	v_cvt_pk_bf16_f32 v48, v56, v57
	v_cvt_pk_bf16_f32 v49, v58, v59
	v_cvt_pk_bf16_f32 v50, v60, v61
	v_cvt_pk_bf16_f32 v51, v62, v63
	v_cvt_pk_bf16_f32 v32, v40, v41
	v_cvt_pk_bf16_f32 v33, v42, v43
	v_cvt_pk_bf16_f32 v35, v46, v47
	s_waitcnt lgkmcnt(1)
	global_store_dwordx4 v[6:7], v[0:3], off
	ds_write_b128 v116, v[48:51] offset:4096
	ds_write_b128 v100, v[32:35] offset:4096
	v_or_b32_e32 v0, 0x100, v129
	v_lshl_add_u32 v35, v0, 4, v132
	v_lshrrev_b32_e32 v6, 3, v0
	ds_read_b128 v[0:3], v35
	v_xor_b32_e32 v8, v6, v128
	v_lshlrev_b32_e32 v14, 7, v6
	v_mov_b32_e32 v15, v193
	v_lshlrev_b32_e32 v8, 4, v8
	v_lshl_add_u64 v[6:7], v[4:5], 0, v[14:15]
	v_and_b32_e32 v16, 0x70, v8
	v_mov_b32_e32 v17, v193
	v_lshl_add_u64 v[6:7], v[6:7], 0, v[16:17]
	s_waitcnt lgkmcnt(0)
	global_store_dwordx4 v[6:7], v[0:3], off
	v_mov_b32_e32 v11, v193
	v_mov_b32_e32 v13, v193
	v_or_b32_e32 v0, 0x140, v129
	v_lshl_add_u32 v34, v0, 4, v132
	v_lshrrev_b32_e32 v6, 3, v0
	ds_read_b128 v[0:3], v34
	v_xor_b32_e32 v8, v6, v128
	v_lshlrev_b32_e32 v10, 7, v6
	v_lshlrev_b32_e32 v8, 4, v8
	v_lshl_add_u64 v[6:7], v[4:5], 0, v[10:11]
	v_and_b32_e32 v12, 0x70, v8
	v_lshl_add_u64 v[6:7], v[6:7], 0, v[12:13]
	s_waitcnt lgkmcnt(0)
	global_store_dwordx4 v[6:7], v[0:3], off
	v_mfma_f32_32x32x16_bf16 v[80:95], v[168:171], v[136:139], v[80:95]
	v_mov_b32_e32 v7, v193
	v_or_b32_e32 v0, 0x180, v129
	v_lshl_add_u32 v33, v0, 4, v132
	v_lshrrev_b32_e32 v6, 3, v0
	ds_read_b128 v[0:3], v33
	v_xor_b32_e32 v8, v6, v128
	v_lshlrev_b32_e32 v6, 7, v6
	v_mfma_f32_32x32x16_bf16 v[64:79], v[172:175], v[136:139], v[64:79]
	v_lshlrev_b32_e32 v8, 4, v8
	v_lshl_add_u64 v[38:39], v[4:5], 0, v[6:7]
	v_and_b32_e32 v8, 0x70, v8
	v_mov_b32_e32 v9, v193
	v_lshl_add_u64 v[38:39], v[38:39], 0, v[8:9]
	s_waitcnt lgkmcnt(0)
	global_store_dwordx4 v[38:39], v[0:3], off
	v_cvt_pk_bf16_f32 v80, v80, v81
	v_cvt_pk_bf16_f32 v81, v82, v83
	v_or_b32_e32 v0, 0x1c0, v129
	v_lshl_add_u32 v32, v0, 4, v132
	v_lshrrev_b32_e32 v1, 3, v0
	ds_read_b128 v[38:41], v32
	v_xor_b32_e32 v2, v1, v128
	v_cvt_pk_bf16_f32 v82, v84, v85
	v_cvt_pk_bf16_f32 v83, v86, v87
	v_cvt_pk_bf16_f32 v64, v64, v65
	v_cvt_pk_bf16_f32 v65, v66, v67
	v_cvt_pk_bf16_f32 v66, v68, v69
	v_cvt_pk_bf16_f32 v67, v70, v71
	v_lshlrev_b32_e32 v0, 7, v1
	v_mov_b32_e32 v1, v193
	v_lshlrev_b32_e32 v2, 4, v2
	ds_write_b128 v135, v[80:83] offset:8192
	v_cvt_pk_bf16_f32 v80, v88, v89
	v_cvt_pk_bf16_f32 v81, v90, v91
	v_cvt_pk_bf16_f32 v82, v92, v93
	v_cvt_pk_bf16_f32 v83, v94, v95
	ds_write_b128 v112, v[64:67] offset:8192
	v_cvt_pk_bf16_f32 v64, v72, v73
	v_cvt_pk_bf16_f32 v65, v74, v75
	v_cvt_pk_bf16_f32 v66, v76, v77
	v_cvt_pk_bf16_f32 v67, v78, v79
	v_lshl_add_u64 v[42:43], v[4:5], 0, v[0:1]
	v_and_b32_e32 v2, 0x70, v2
	v_mov_b32_e32 v3, v193
	ds_write_b128 v116, v[80:83] offset:8192
	ds_write_b128 v100, v[64:67] offset:8192
	v_lshl_add_u64 v[42:43], v[42:43], 0, v[2:3]
	s_waitcnt lgkmcnt(4)
	global_store_dwordx4 v[42:43], v[38:41], off
	ds_read_b128 v[38:41], v37 offset:8192
	v_lshl_add_u64 v[4:5], v[4:5], 0, s[16:17]
	v_lshl_add_u64 v[42:43], v[4:5], 0, v[192:193]
	v_lshl_add_u64 v[30:31], v[42:43], 0, v[30:31]
	v_lshl_add_u64 v[26:27], v[4:5], 0, v[26:27]
	s_waitcnt lgkmcnt(0)
	global_store_dwordx4 v[30:31], v[38:41], off
	ds_read_b128 v[38:41], v44 offset:8192
	v_lshl_add_u64 v[26:27], v[26:27], 0, v[28:29]
	v_lshl_add_u64 v[22:23], v[4:5], 0, v[22:23]
	v_lshl_add_u64 v[22:23], v[22:23], 0, v[24:25]
	v_lshl_add_u64 v[18:19], v[4:5], 0, v[18:19]
	s_waitcnt lgkmcnt(0)
	global_store_dwordx4 v[26:27], v[38:41], off
	ds_read_b128 v[26:29], v45 offset:8192
	v_lshl_add_u64 v[18:19], v[18:19], 0, v[20:21]
	v_lshl_add_u64 v[14:15], v[4:5], 0, v[14:15]
	v_lshl_add_u64 v[14:15], v[14:15], 0, v[16:17]
	v_lshl_add_u64 v[10:11], v[4:5], 0, v[10:11]
	s_waitcnt lgkmcnt(0)
	global_store_dwordx4 v[22:23], v[26:29], off
	ds_read_b128 v[22:25], v36 offset:8192
	v_lshl_add_u64 v[10:11], v[10:11], 0, v[12:13]
	v_lshl_add_u64 v[6:7], v[4:5], 0, v[6:7]
	v_lshl_add_u64 v[6:7], v[6:7], 0, v[8:9]
	v_lshl_add_u64 v[0:1], v[4:5], 0, v[0:1]
	s_waitcnt lgkmcnt(0)
	global_store_dwordx4 v[18:19], v[22:25], off
	ds_read_b128 v[18:21], v35 offset:8192
	v_lshl_add_u64 v[0:1], v[0:1], 0, v[2:3]
	s_waitcnt lgkmcnt(0)
	global_store_dwordx4 v[14:15], v[18:21], off
	ds_read_b128 v[14:17], v34 offset:8192
	s_waitcnt lgkmcnt(0)
	global_store_dwordx4 v[10:11], v[14:17], off
	ds_read_b128 v[10:13], v33 offset:8192
	s_waitcnt lgkmcnt(0)
	global_store_dwordx4 v[6:7], v[10:13], off
	ds_read_b128 v[6:9], v32 offset:8192
	s_waitcnt lgkmcnt(0)
	global_store_dwordx4 v[0:1], v[6:9], off
	s_branch .LBB0_185

; __global__ void __launch_bounds__(NTHREADS, 2) mega(Params p_, int ph_lo, int ph_hi) {
	.amdhsa_kernel _Z4mega6Paramsii
		.amdhsa_group_segment_fixed_size 32
		.amdhsa_private_segment_fixed_size 0
		.amdhsa_kernarg_size 536
		.amdhsa_user_sgpr_count 2
		.amdhsa_user_sgpr_dispatch_ptr 0
		.amdhsa_user_sgpr_queue_ptr 0
		.amdhsa_user_sgpr_kernarg_segment_ptr 1
		.amdhsa_user_sgpr_dispatch_id 0
		.amdhsa_user_sgpr_kernarg_preload_length 0
		.amdhsa_user_sgpr_kernarg_preload_offset 0
		.amdhsa_user_sgpr_private_segment_size 0
		.amdhsa_uses_dynamic_stack 0
		.amdhsa_enable_private_segment 0
		.amdhsa_system_sgpr_workgroup_id_x 1
		.amdhsa_system_sgpr_workgroup_id_y 0
		.amdhsa_system_sgpr_workgroup_id_z 0
		.amdhsa_system_sgpr_workgroup_info 0
		.amdhsa_system_vgpr_workitem_id 2
		.amdhsa_next_free_vgpr 256
		.amdhsa_next_free_sgpr 102
		.amdhsa_accum_offset 256
		.amdhsa_reserve_vcc 1
		.amdhsa_float_round_mode_32 0
		.amdhsa_float_round_mode_16_64 0
		.amdhsa_float_denorm_mode_32 3
		.amdhsa_float_denorm_mode_16_64 3
		.amdhsa_dx10_clamp 1
		.amdhsa_ieee_mode 1
		.amdhsa_fp16_overflow 0
		.amdhsa_tg_split 0
		.amdhsa_exception_fp_ieee_invalid_op 0
		.amdhsa_exception_fp_denorm_src 0
		.amdhsa_exception_fp_ieee_div_zero 0
		.amdhsa_exception_fp_ieee_overflow 0
		.amdhsa_exception_fp_ieee_underflow 0
		.amdhsa_exception_fp_ieee_inexact 0
		.amdhsa_exception_int_div_zero 0
	.end_amdhsa_kernel

; __global__ void __launch_bounds__(NTHREADS, 2) mega(Params p_, int ph_lo, int ph_hi) {
amdhsa.kernels:
  - .agpr_count:     0
    .args:
      - .offset:         0
        .size:           272
        .value_kind:     by_value
      - .offset:         272
        .size:           4
        .value_kind:     by_value
      - .offset:         276
        .size:           4
        .value_kind:     by_value
      - .offset:         280
        .size:           4
        .value_kind:     hidden_block_count_x
      - .offset:         284
        .size:           4
        .value_kind:     hidden_block_count_y
      - .offset:         288
        .size:           4
        .value_kind:     hidden_block_count_z
      - .offset:         292
        .size:           2
        .value_kind:     hidden_group_size_x
      - .offset:         294
        .size:           2
        .value_kind:     hidden_group_size_y
      - .offset:         296
        .size:           2
        .value_kind:     hidden_group_size_z
      - .offset:         298
        .size:           2
        .value_kind:     hidden_remainder_x
      - .offset:         300
        .size:           2
        .value_kind:     hidden_remainder_y
      - .offset:         302
        .size:           2
        .value_kind:     hidden_remainder_z
      - .offset:         320
        .size:           8
        .value_kind:     hidden_global_offset_x
      - .offset:         328
        .size:           8
        .value_kind:     hidden_global_offset_y
      - .offset:         336
        .size:           8
        .value_kind:     hidden_global_offset_z
      - .offset:         344
        .size:           2
        .value_kind:     hidden_grid_dims
      - .offset:         368
        .size:           8
        .value_kind:     hidden_multigrid_sync_arg
      - .offset:         400
        .size:           4
        .value_kind:     hidden_dynamic_lds_size
    .group_segment_fixed_size: 32
    .kernarg_segment_align: 8
    .kernarg_segment_size: 536
    .language:       OpenCL C
    .language_version:
      - 2
      - 0
    .max_flat_workgroup_size: 256
    .name:           _Z4mega6Paramsii
    .private_segment_fixed_size: 0
    .sgpr_count:     108
    .sgpr_spill_count: 104
    .symbol:         _Z4mega6Paramsii.kd
    .uniform_work_group_size: 1
    .uses_dynamic_stack: false
    .vgpr_count:     256
    .vgpr_spill_count: 0
    .wavefront_size: 64
